# GEMM K-loops: first iteration peeled with SrcC=0 (no per-tile accumulator zero-init)
# speedup vs baseline: 1.0071x; 1.0071x over previous
; #define PG8_STAGE(bufoff, gbase, voff) do { _Pragma("unroll") for (int _i = 0; _i < 2; ++_i) \
;         __builtin_amdgcn_global_load_lds((const unsigned*)((const char*)(gbase) + (voff)[_i]), (LAS unsigned*)(lds + (bufoff) + ldsw + _i * 8192), 16, 0, 0); } while (0)
; #define PG8_LDA(dst, b, h) do { _Pragma("unroll") for (int m = 0; m < 4; ++m) _Pragma("unroll") for (int k = 0; k < 2; ++k) dst[m][k] = *(const LAS bf16x8*)(lds + PG8_SA(b, h) + aoff + m * 2048 + k * 1024); } while (0)
; #define PG8_LDB(dst, b, h) do { _Pragma("unroll") for (int n = 0; n < 2; ++n) _Pragma("unroll") for (int k = 0; k < 2; ++k) dst[n][k] = *(const LAS bf16x8*)(lds + PG8_SB(b, h) + boff + n * 2048 + k * 1024); } while (0)
; #define PG8_MMA(ai, bj, At, Bt) do { __builtin_amdgcn_s_setprio(1); _Pragma("unroll") for (int m = 0; m < 4; ++m) _Pragma("unroll") for (int n = 0; n < 2; ++n) _Pragma("unroll") for (int k = 0; k < 2; ++k) \
;         acc[ai][bj][m][n] = __builtin_amdgcn_mfma_f32_16x16x32_bf16(Bt[n][k], At[m][k], acc[ai][bj][m][n], 0, 0, 0); __builtin_amdgcn_s_setprio(0); } while (0)
; #define PG8_WAIT_L(n) asm volatile("s_waitcnt lgkmcnt(" #n ")" ::: "memory")
; #define PG8_BAR __builtin_amdgcn_s_barrier()
; #define PG8_SCHED __builtin_amdgcn_sched_barrier(0)
; template <class Epi>
; DI void gemm_phase(LAS unsigned char* lds, const Gemm g, const StaticOrder& S, const Epi& E) {
;     ...
;         for (int t = 0; t < nt; t += 2) {
;             const bool last = (t == nt - 2);
;             const char* a1 = cA + (size_t)(t + 1) * kstep;
;             const char* a2 = last ? nA : cA + (size_t)(t + 2) * kstep; const char* b2 = last ? nB : cB + (size_t)(t + 2) * kstep;
;             const char* a3 = a2 + kstep; const char* b3 = b2 + kstep;
;             PG8_LDB(B0, 0, 0); PG8_SCHED; PG8_LDA(At, 0, 0); PG8_STAGE(PG8_SA(1, 1), a1 + hstep, voffA);
;             PG8_WAIT_L(8); PG8_BAR; PG8_WAIT_L(0); PG8_MMA(0, 0, At, B0); PG8_BAR; PG8_SCHED;
;             PG8_LDB(B1, 0, 1); PG8_STAGE(PG8_SB(0, 0), b2, voffB);
;             PG8_BAR; PG8_WAIT_L(0); PG8_MMA(0, 1, At, B1); PG8_BAR;
;             PG8_LDA(At, 0, 1); PG8_STAGE(PG8_SA(0, 0), a2, voffA);
;             PG8_BAR; PG8_WAIT_L(0); PG8_MMA(1, 0, At, B0); PG8_BAR; PG8_SCHED;
.LBB0_210:
	s_ashr_i32 s17, s16, 31
	v_cmp_lt_i64_e32 vcc, s[18:19], v[140:141]
	s_lshl_b64 s[18:19], s[16:17], 19
	s_add_u32 s18, s43, s18
	s_addc_u32 s19, s44, s19
	s_and_b64 s[22:23], vcc, exec
	s_cselect_b32 s17, s19, s25
	s_cselect_b32 s76, s18, s24
	s_ashr_i32 s15, s14, 31
	s_lshl_b64 s[22:23], s[14:15], 19
	s_add_u32 s22, s30, s22
	s_addc_u32 s23, s31, s23
	s_and_b64 s[40:41], vcc, exec
	s_cselect_b32 s15, s23, s39
	s_cselect_b32 s77, s22, s38
	s_add_u32 s24, s24, 0x40080
	s_addc_u32 s25, s25, 0
	s_add_u32 s78, s38, 0x100
	s_addc_u32 s79, s39, 0
	s_mov_b32 s80, -2
	ds_read_b128 v[150:153], v147
	ds_read_b128 v[154:157], v147 offset:1024
	ds_read_b128 v[158:161], v147 offset:2048
	ds_read_b128 v[162:165], v147 offset:3072
	s_add_u32 s38, s24, 0xfffc0080
	s_addc_u32 s39, s25, -1
	s_cmp_eq_u32 s80, 12
	s_cselect_b32 s41, s17, s39
	s_cselect_b32 s40, s76, s38
	s_cselect_b32 s39, s15, s79
	s_cselect_b32 s38, s77, s78
	v_lshl_add_u64 v[178:179], s[24:25], 0, v[136:137]
	s_add_i32 m0, s13, 0xc000
	ds_read_b128 v[166:169], v148
	ds_read_b128 v[170:173], v148 offset:1024
	ds_read_b128 v[174:177], v148 offset:2048
	ds_read_b128 v[182:185], v148 offset:3072
	ds_read_b128 v[186:189], v148 offset:4096
	ds_read_b128 v[190:193], v148 offset:5120
	ds_read_b128 v[194:197], v148 offset:6144
	ds_read_b128 v[198:201], v148 offset:7168
	global_load_lds_dwordx4 v[178:179], off
	v_lshl_add_u64 v[178:179], s[24:25], 0, v[138:139]
	s_add_i32 m0, s13, 0xe000
	s_nop 0
	global_load_lds_dwordx4 v[178:179], off
	s_waitcnt lgkmcnt(8)
	s_barrier
	s_waitcnt lgkmcnt(0)
	s_waitcnt lgkmcnt(0)
	v_mfma_f32_16x16x32_bf16 v[124:127], v[150:153], v[166:169], 0
	v_mfma_f32_16x16x32_bf16 v[120:123], v[158:161], v[166:169], 0
	v_mfma_f32_16x16x32_bf16 v[116:119], v[150:153], v[174:177], 0
	v_mfma_f32_16x16x32_bf16 v[112:115], v[158:161], v[174:177], 0
	v_mfma_f32_16x16x32_bf16 v[100:103], v[150:153], v[186:189], 0
	v_mfma_f32_16x16x32_bf16 v[96:99], v[158:161], v[186:189], 0
	v_mfma_f32_16x16x32_bf16 v[84:87], v[150:153], v[194:197], 0
	v_mfma_f32_16x16x32_bf16 v[80:83], v[158:161], v[194:197], 0
	v_mfma_f32_16x16x32_bf16 v[124:127], v[154:157], v[170:173], v[124:127]
	v_mfma_f32_16x16x32_bf16 v[120:123], v[162:165], v[170:173], v[120:123]
	v_mfma_f32_16x16x32_bf16 v[116:119], v[154:157], v[182:185], v[116:119]
	v_mfma_f32_16x16x32_bf16 v[112:115], v[162:165], v[182:185], v[112:115]
	v_mfma_f32_16x16x32_bf16 v[100:103], v[154:157], v[190:193], v[100:103]
	v_mfma_f32_16x16x32_bf16 v[96:99], v[162:165], v[190:193], v[96:99]
	v_mfma_f32_16x16x32_bf16 v[84:87], v[154:157], v[198:201], v[84:87]
	v_mfma_f32_16x16x32_bf16 v[80:83], v[162:165], v[198:201], v[80:83]
	s_barrier
	s_add_i32 s81, s71, s45
	v_lshl_add_u64 v[178:179], s[38:39], 0, v[132:133]
	s_mov_b32 m0, s81
	ds_read_b128 v[202:205], v149
	ds_read_b128 v[206:209], v149 offset:1024
	ds_read_b128 v[210:213], v149 offset:2048
	ds_read_b128 v[214:217], v149 offset:3072
	global_load_lds_dwordx4 v[178:179], off
	v_lshl_add_u64 v[218:219], s[38:39], 0, v[128:129]
	s_add_i32 m0, s81, 0x2000
	s_nop 0
	global_load_lds_dwordx4 v[218:219], off
	s_barrier
	s_waitcnt lgkmcnt(0)
	s_waitcnt lgkmcnt(0)
	v_mfma_f32_16x16x32_bf16 v[108:111], v[202:205], v[166:169], 0
	v_mfma_f32_16x16x32_bf16 v[104:107], v[210:213], v[166:169], 0
	v_mfma_f32_16x16x32_bf16 v[92:95], v[202:205], v[174:177], 0
	v_mfma_f32_16x16x32_bf16 v[88:91], v[210:213], v[174:177], 0
	v_mfma_f32_16x16x32_bf16 v[76:79], v[202:205], v[186:189], 0
	v_mfma_f32_16x16x32_bf16 v[72:75], v[210:213], v[186:189], 0
	v_mfma_f32_16x16x32_bf16 v[68:71], v[202:205], v[194:197], 0
	v_mfma_f32_16x16x32_bf16 v[64:67], v[210:213], v[194:197], 0
	v_mfma_f32_16x16x32_bf16 v[108:111], v[206:209], v[170:173], v[108:111]
	v_mfma_f32_16x16x32_bf16 v[104:107], v[214:217], v[170:173], v[104:107]
	v_mfma_f32_16x16x32_bf16 v[92:95], v[206:209], v[182:185], v[92:95]
	v_mfma_f32_16x16x32_bf16 v[88:91], v[214:217], v[182:185], v[88:91]
	v_mfma_f32_16x16x32_bf16 v[76:79], v[206:209], v[190:193], v[76:79]
	v_mfma_f32_16x16x32_bf16 v[72:75], v[214:217], v[190:193], v[72:75]
	v_mfma_f32_16x16x32_bf16 v[68:71], v[206:209], v[198:201], v[68:71]
	v_mfma_f32_16x16x32_bf16 v[64:67], v[214:217], v[198:201], v[64:67]
	s_mov_b32 m0, s13
	v_lshl_add_u64 v[220:221], s[40:41], 0, v[134:135]
	s_barrier
	ds_read_b128 v[166:169], v148 offset:16384
	ds_read_b128 v[170:173], v148 offset:17408
	ds_read_b128 v[174:177], v148 offset:18432
	ds_read_b128 v[182:185], v148 offset:19456
	ds_read_b128 v[186:189], v148 offset:20480
	ds_read_b128 v[190:193], v148 offset:21504
	ds_read_b128 v[194:197], v148 offset:22528
	ds_read_b128 v[198:201], v148 offset:23552
	global_load_lds_dwordx4 v[220:221], off
	v_lshl_add_u64 v[222:223], s[40:41], 0, v[130:131]
	s_mov_b32 m0, s48
	s_nop 0
	global_load_lds_dwordx4 v[222:223], off
	s_barrier
	s_waitcnt lgkmcnt(0)
	s_waitcnt lgkmcnt(0)
	v_mfma_f32_16x16x32_bf16 v[60:63], v[150:153], v[166:169], 0
	v_mfma_f32_16x16x32_bf16 v[56:59], v[158:161], v[166:169], 0
	v_mfma_f32_16x16x32_bf16 v[52:55], v[150:153], v[174:177], 0
	v_mfma_f32_16x16x32_bf16 v[48:51], v[158:161], v[174:177], 0
	v_mfma_f32_16x16x32_bf16 v[36:39], v[150:153], v[186:189], 0
	v_mfma_f32_16x16x32_bf16 v[32:35], v[158:161], v[186:189], 0
	v_mfma_f32_16x16x32_bf16 v[20:23], v[150:153], v[194:197], 0
	v_mfma_f32_16x16x32_bf16 v[16:19], v[158:161], v[194:197], 0
	v_mfma_f32_16x16x32_bf16 v[60:63], v[154:157], v[170:173], v[60:63]
	v_mfma_f32_16x16x32_bf16 v[56:59], v[162:165], v[170:173], v[56:59]
	v_mfma_f32_16x16x32_bf16 v[52:55], v[154:157], v[182:185], v[52:55]
	v_mfma_f32_16x16x32_bf16 v[48:51], v[162:165], v[182:185], v[48:51]
	v_mfma_f32_16x16x32_bf16 v[36:39], v[154:157], v[190:193], v[36:39]
	v_mfma_f32_16x16x32_bf16 v[32:35], v[162:165], v[190:193], v[32:35]
	v_mfma_f32_16x16x32_bf16 v[20:23], v[154:157], v[198:201], v[20:23]
	v_mfma_f32_16x16x32_bf16 v[16:19], v[162:165], v[198:201], v[16:19]
	s_barrier
; #define PG8_STAGE(bufoff, gbase, voff) do { _Pragma("unroll") for (int _i = 0; _i < 2; ++_i) \
;         __builtin_amdgcn_global_load_lds((const unsigned*)((const char*)(gbase) + (voff)[_i]), (LAS unsigned*)(lds + (bufoff) + ldsw + _i * 8192), 16, 0, 0); } while (0)
; #define PG8_LDA(dst, b, h) do { _Pragma("unroll") for (int m = 0; m < 4; ++m) _Pragma("unroll") for (int k = 0; k < 2; ++k) dst[m][k] = *(const LAS bf16x8*)(lds + PG8_SA(b, h) + aoff + m * 2048 + k * 1024); } while (0)
; #define PG8_LDB(dst, b, h) do { _Pragma("unroll") for (int n = 0; n < 2; ++n) _Pragma("unroll") for (int k = 0; k < 2; ++k) dst[n][k] = *(const LAS bf16x8*)(lds + PG8_SB(b, h) + boff + n * 2048 + k * 1024); } while (0)
; #define PG8_MMA(ai, bj, At, Bt) do { __builtin_amdgcn_s_setprio(1); _Pragma("unroll") for (int m = 0; m < 4; ++m) _Pragma("unroll") for (int n = 0; n < 2; ++n) _Pragma("unroll") for (int k = 0; k < 2; ++k) \
;         acc[ai][bj][m][n] = __builtin_amdgcn_mfma_f32_16x16x32_bf16(Bt[n][k], At[m][k], acc[ai][bj][m][n], 0, 0, 0); __builtin_amdgcn_s_setprio(0); } while (0)
; #define PG8_WAIT_V(n) asm volatile("s_waitcnt vmcnt(" #n ")" ::: "memory")
; #define PG8_WAIT_L(n) asm volatile("s_waitcnt lgkmcnt(" #n ")" ::: "memory")
; #define PG8_BAR __builtin_amdgcn_s_barrier()
; #define PG8_SCHED __builtin_amdgcn_sched_barrier(0)
; template <class Epi>
; DI void gemm_phase(LAS unsigned char* lds, const Gemm g, const StaticOrder& S, const Epi& E) {
;     ...
;             PG8_STAGE(PG8_SB(0, 1), b2 + hstep, voffB);
;             PG8_WAIT_V(6); PG8_BAR; PG8_MMA(1, 1, At, B1); PG8_BAR;
;             PG8_LDB(B0, 1, 0); PG8_SCHED; PG8_LDA(At, 1, 0); PG8_STAGE(PG8_SA(0, 1), a2 + hstep, voffA);
;             PG8_WAIT_L(8); PG8_BAR; PG8_WAIT_L(0); PG8_MMA(0, 0, At, B0); PG8_BAR; PG8_SCHED;
;             PG8_LDB(B1, 1, 1); PG8_STAGE(PG8_SB(1, 0), b3, voffB);
	s_add_u32 s82, s38, 0x40000
	s_addc_u32 s83, s39, 0
	s_add_i32 s81, s72, s45
	v_lshl_add_u64 v[150:151], s[82:83], 0, v[132:133]
	s_mov_b32 m0, s81
	s_nop 0
	global_load_lds_dwordx4 v[150:151], off
	v_lshl_add_u64 v[150:151], s[82:83], 0, v[128:129]
	s_add_i32 m0, s81, 0x2000
	s_nop 0
	global_load_lds_dwordx4 v[150:151], off
	s_waitcnt vmcnt(6)
	s_barrier
	v_mfma_f32_16x16x32_bf16 v[44:47], v[202:205], v[166:169], 0
	v_mfma_f32_16x16x32_bf16 v[40:43], v[210:213], v[166:169], 0
	v_mfma_f32_16x16x32_bf16 v[28:31], v[202:205], v[174:177], 0
	v_mfma_f32_16x16x32_bf16 v[24:27], v[210:213], v[174:177], 0
	v_mfma_f32_16x16x32_bf16 v[12:15], v[202:205], v[186:189], 0
	v_mfma_f32_16x16x32_bf16 v[8:11], v[210:213], v[186:189], 0
	v_mfma_f32_16x16x32_bf16 v[4:7], v[202:205], v[194:197], 0
	v_mfma_f32_16x16x32_bf16 v[0:3], v[210:213], v[194:197], 0
	v_mfma_f32_16x16x32_bf16 v[44:47], v[206:209], v[170:173], v[44:47]
	v_mfma_f32_16x16x32_bf16 v[40:43], v[214:217], v[170:173], v[40:43]
	v_mfma_f32_16x16x32_bf16 v[28:31], v[206:209], v[182:185], v[28:31]
	v_mfma_f32_16x16x32_bf16 v[24:27], v[214:217], v[182:185], v[24:27]
	v_mfma_f32_16x16x32_bf16 v[12:15], v[206:209], v[190:193], v[12:15]
	v_mfma_f32_16x16x32_bf16 v[8:11], v[214:217], v[190:193], v[8:11]
	v_mfma_f32_16x16x32_bf16 v[4:7], v[206:209], v[198:201], v[4:7]
	v_mfma_f32_16x16x32_bf16 v[0:3], v[214:217], v[198:201], v[0:3]
	s_add_i32 s81, 0, 0x18000
	v_add_u32_e32 v162, s81, v145
	s_barrier
	ds_read_b128 v[150:153], v162
	ds_read_b128 v[154:157], v162 offset:1024
	ds_read_b128 v[158:161], v162 offset:2048
	ds_read_b128 v[162:165], v162 offset:3072
	s_add_u32 s40, s40, 0x40000
	s_addc_u32 s41, s41, 0
	s_mov_b32 m0, s49
	v_lshl_add_u64 v[202:203], s[40:41], 0, v[134:135]
	ds_read_b128 v[166:169], v148 offset:32768
	ds_read_b128 v[170:173], v148 offset:33792
	ds_read_b128 v[174:177], v148 offset:34816
	ds_read_b128 v[182:185], v148 offset:35840
	ds_read_b128 v[186:189], v148 offset:36864
	ds_read_b128 v[190:193], v148 offset:37888
	ds_read_b128 v[194:197], v148 offset:38912
	ds_read_b128 v[198:201], v148 offset:39936
	global_load_lds_dwordx4 v[202:203], off
	v_lshl_add_u64 v[202:203], s[40:41], 0, v[130:131]
	s_mov_b32 m0, s50
	s_nop 0
	global_load_lds_dwordx4 v[202:203], off
	s_waitcnt lgkmcnt(8)
	s_barrier
	s_waitcnt lgkmcnt(0)
	s_waitcnt lgkmcnt(0)
	v_mfma_f32_16x16x32_bf16 v[124:127], v[150:153], v[166:169], v[124:127]
	v_mfma_f32_16x16x32_bf16 v[120:123], v[158:161], v[166:169], v[120:123]
	v_mfma_f32_16x16x32_bf16 v[116:119], v[150:153], v[174:177], v[116:119]
	v_mfma_f32_16x16x32_bf16 v[112:115], v[158:161], v[174:177], v[112:115]
	v_mfma_f32_16x16x32_bf16 v[100:103], v[150:153], v[186:189], v[100:103]
	v_mfma_f32_16x16x32_bf16 v[96:99], v[158:161], v[186:189], v[96:99]
	v_mfma_f32_16x16x32_bf16 v[84:87], v[150:153], v[194:197], v[84:87]
	v_mfma_f32_16x16x32_bf16 v[80:83], v[158:161], v[194:197], v[80:83]
	v_mfma_f32_16x16x32_bf16 v[124:127], v[154:157], v[170:173], v[124:127]
	v_mfma_f32_16x16x32_bf16 v[120:123], v[162:165], v[170:173], v[120:123]
	v_mfma_f32_16x16x32_bf16 v[116:119], v[154:157], v[182:185], v[116:119]
	v_mfma_f32_16x16x32_bf16 v[112:115], v[162:165], v[182:185], v[112:115]
	v_mfma_f32_16x16x32_bf16 v[100:103], v[154:157], v[190:193], v[100:103]
	v_mfma_f32_16x16x32_bf16 v[96:99], v[162:165], v[190:193], v[96:99]
	v_mfma_f32_16x16x32_bf16 v[84:87], v[154:157], v[198:201], v[84:87]
	v_mfma_f32_16x16x32_bf16 v[80:83], v[162:165], v[198:201], v[80:83]
	s_barrier
	s_add_i32 s40, 0, 0x1c000
	s_add_i32 s41, s81, s45
	v_add_u32_e32 v214, s40, v145
	v_lshl_add_u64 v[178:179], v[178:179], 0, s[8:9]
	s_mov_b32 m0, s41
	ds_read_b128 v[202:205], v214
	ds_read_b128 v[206:209], v214 offset:1024
	ds_read_b128 v[210:213], v214 offset:2048
	ds_read_b128 v[214:217], v214 offset:3072
	global_load_lds_dwordx4 v[178:179], off
	v_lshl_add_u64 v[178:179], v[218:219], 0, s[8:9]
	s_add_i32 m0, s41, 0x2000
	s_nop 0
	global_load_lds_dwordx4 v[178:179], off
	s_barrier
; #define PG8_STAGE(bufoff, gbase, voff) do { _Pragma("unroll") for (int _i = 0; _i < 2; ++_i) \
;         __builtin_amdgcn_global_load_lds((const unsigned*)((const char*)(gbase) + (voff)[_i]), (LAS unsigned*)(lds + (bufoff) + ldsw + _i * 8192), 16, 0, 0); } while (0)
; #define PG8_LDA(dst, b, h) do { _Pragma("unroll") for (int m = 0; m < 4; ++m) _Pragma("unroll") for (int k = 0; k < 2; ++k) dst[m][k] = *(const LAS bf16x8*)(lds + PG8_SA(b, h) + aoff + m * 2048 + k * 1024); } while (0)
; #define PG8_MMA(ai, bj, At, Bt) do { __builtin_amdgcn_s_setprio(1); _Pragma("unroll") for (int m = 0; m < 4; ++m) _Pragma("unroll") for (int n = 0; n < 2; ++n) _Pragma("unroll") for (int k = 0; k < 2; ++k) \
;         acc[ai][bj][m][n] = __builtin_amdgcn_mfma_f32_16x16x32_bf16(Bt[n][k], At[m][k], acc[ai][bj][m][n], 0, 0, 0); __builtin_amdgcn_s_setprio(0); } while (0)
; #define PG8_WAIT_V(n) asm volatile("s_waitcnt vmcnt(" #n ")" ::: "memory")
; #define PG8_WAIT_L(n) asm volatile("s_waitcnt lgkmcnt(" #n ")" ::: "memory")
; #define PG8_BAR __builtin_amdgcn_s_barrier()
; #define PG8_SCHED __builtin_amdgcn_sched_barrier(0)
; template <class Epi>
; DI void gemm_phase(LAS unsigned char* lds, const Gemm g, const StaticOrder& S, const Epi& E) {
;     ...
;             PG8_BAR; PG8_WAIT_L(0); PG8_MMA(0, 1, At, B1); PG8_BAR;
;             PG8_LDA(At, 1, 1); PG8_STAGE(PG8_SA(1, 0), a3, voffA);
;             PG8_BAR; PG8_WAIT_L(0); PG8_MMA(1, 0, At, B0); PG8_BAR; PG8_SCHED;
;             PG8_STAGE(PG8_SB(1, 1), b3 + hstep, voffB);
;             PG8_WAIT_V(6); PG8_BAR; PG8_MMA(1, 1, At, B1); PG8_BAR;
;         }
	s_waitcnt lgkmcnt(0)
	s_waitcnt lgkmcnt(0)
	v_mfma_f32_16x16x32_bf16 v[108:111], v[202:205], v[166:169], v[108:111]
	v_mfma_f32_16x16x32_bf16 v[104:107], v[210:213], v[166:169], v[104:107]
	v_mfma_f32_16x16x32_bf16 v[92:95], v[202:205], v[174:177], v[92:95]
	v_mfma_f32_16x16x32_bf16 v[88:91], v[210:213], v[174:177], v[88:91]
	v_mfma_f32_16x16x32_bf16 v[76:79], v[202:205], v[186:189], v[76:79]
	v_mfma_f32_16x16x32_bf16 v[72:75], v[210:213], v[186:189], v[72:75]
	v_mfma_f32_16x16x32_bf16 v[68:71], v[202:205], v[194:197], v[68:71]
	v_mfma_f32_16x16x32_bf16 v[64:67], v[210:213], v[194:197], v[64:67]
	v_mfma_f32_16x16x32_bf16 v[108:111], v[206:209], v[170:173], v[108:111]
	v_mfma_f32_16x16x32_bf16 v[104:107], v[214:217], v[170:173], v[104:107]
	v_mfma_f32_16x16x32_bf16 v[92:95], v[206:209], v[182:185], v[92:95]
	v_mfma_f32_16x16x32_bf16 v[88:91], v[214:217], v[182:185], v[88:91]
	v_mfma_f32_16x16x32_bf16 v[76:79], v[206:209], v[190:193], v[76:79]
	v_mfma_f32_16x16x32_bf16 v[72:75], v[214:217], v[190:193], v[72:75]
	v_mfma_f32_16x16x32_bf16 v[68:71], v[206:209], v[198:201], v[68:71]
	v_mfma_f32_16x16x32_bf16 v[64:67], v[214:217], v[198:201], v[64:67]
	s_mov_b32 m0, s66
	v_lshl_add_u64 v[178:179], v[220:221], 0, s[8:9]
	s_barrier
	ds_read_b128 v[166:169], v148 offset:49152
	ds_read_b128 v[170:173], v148 offset:50176
	ds_read_b128 v[174:177], v148 offset:51200
	ds_read_b128 v[182:185], v148 offset:52224
	ds_read_b128 v[186:189], v148 offset:53248
	ds_read_b128 v[190:193], v148 offset:54272
	ds_read_b128 v[194:197], v148 offset:55296
	ds_read_b128 v[198:201], v148 offset:56320
	global_load_lds_dwordx4 v[178:179], off
	v_lshl_add_u64 v[178:179], v[222:223], 0, s[8:9]
	s_mov_b32 m0, s67
	s_nop 0
	global_load_lds_dwordx4 v[178:179], off
	s_barrier
	s_waitcnt lgkmcnt(0)
	s_waitcnt lgkmcnt(0)
	v_mfma_f32_16x16x32_bf16 v[60:63], v[150:153], v[166:169], v[60:63]
	v_mfma_f32_16x16x32_bf16 v[56:59], v[158:161], v[166:169], v[56:59]
	v_mfma_f32_16x16x32_bf16 v[52:55], v[150:153], v[174:177], v[52:55]
	v_mfma_f32_16x16x32_bf16 v[48:51], v[158:161], v[174:177], v[48:51]
	v_mfma_f32_16x16x32_bf16 v[36:39], v[150:153], v[186:189], v[36:39]
	v_mfma_f32_16x16x32_bf16 v[32:35], v[158:161], v[186:189], v[32:35]
	v_mfma_f32_16x16x32_bf16 v[20:23], v[150:153], v[194:197], v[20:23]
	v_mfma_f32_16x16x32_bf16 v[16:19], v[158:161], v[194:197], v[16:19]
	v_mfma_f32_16x16x32_bf16 v[60:63], v[154:157], v[170:173], v[60:63]
	v_mfma_f32_16x16x32_bf16 v[56:59], v[162:165], v[170:173], v[56:59]
	v_mfma_f32_16x16x32_bf16 v[52:55], v[154:157], v[182:185], v[52:55]
	v_mfma_f32_16x16x32_bf16 v[48:51], v[162:165], v[182:185], v[48:51]
	v_mfma_f32_16x16x32_bf16 v[36:39], v[154:157], v[190:193], v[36:39]
	v_mfma_f32_16x16x32_bf16 v[32:35], v[162:165], v[190:193], v[32:35]
	v_mfma_f32_16x16x32_bf16 v[20:23], v[154:157], v[198:201], v[20:23]
	v_mfma_f32_16x16x32_bf16 v[16:19], v[162:165], v[198:201], v[16:19]
	s_barrier
	s_add_u32 s38, s38, 0x40080
	s_addc_u32 s39, s39, 0
	s_add_i32 s40, s40, s45
	v_lshl_add_u64 v[150:151], s[38:39], 0, v[132:133]
	s_mov_b32 m0, s40
	s_nop 0
	global_load_lds_dwordx4 v[150:151], off
	v_lshl_add_u64 v[150:151], s[38:39], 0, v[128:129]
	s_add_i32 m0, s40, 0x2000
	s_nop 0
	global_load_lds_dwordx4 v[150:151], off
	s_waitcnt vmcnt(6)
	s_barrier
	v_mfma_f32_16x16x32_bf16 v[44:47], v[202:205], v[166:169], v[44:47]
	v_mfma_f32_16x16x32_bf16 v[40:43], v[210:213], v[166:169], v[40:43]
	v_mfma_f32_16x16x32_bf16 v[28:31], v[202:205], v[174:177], v[28:31]
	v_mfma_f32_16x16x32_bf16 v[24:27], v[210:213], v[174:177], v[24:27]
	v_mfma_f32_16x16x32_bf16 v[12:15], v[202:205], v[186:189], v[12:15]
	v_mfma_f32_16x16x32_bf16 v[8:11], v[210:213], v[186:189], v[8:11]
	v_mfma_f32_16x16x32_bf16 v[4:7], v[202:205], v[194:197], v[4:7]
	v_mfma_f32_16x16x32_bf16 v[0:3], v[210:213], v[194:197], v[0:3]
	v_mfma_f32_16x16x32_bf16 v[44:47], v[206:209], v[170:173], v[44:47]
	v_mfma_f32_16x16x32_bf16 v[40:43], v[214:217], v[170:173], v[40:43]
	v_mfma_f32_16x16x32_bf16 v[28:31], v[206:209], v[182:185], v[28:31]
	v_mfma_f32_16x16x32_bf16 v[24:27], v[214:217], v[182:185], v[24:27]
	v_mfma_f32_16x16x32_bf16 v[12:15], v[206:209], v[190:193], v[12:15]
	v_mfma_f32_16x16x32_bf16 v[8:11], v[214:217], v[190:193], v[8:11]
	v_mfma_f32_16x16x32_bf16 v[4:7], v[206:209], v[198:201], v[4:7]
	v_mfma_f32_16x16x32_bf16 v[0:3], v[214:217], v[198:201], v[0:3]
	s_add_i32 s80, s80, 2
	s_add_u32 s24, s24, 0x100
	s_addc_u32 s25, s25, 0
	s_add_u32 s78, s78, 0x100
	s_addc_u32 s79, s79, 0
	s_cmp_gt_u32 s80, 13
	s_barrier

; #define PG8_STAGE(bufoff, gbase, voff) do { _Pragma("unroll") for (int _i = 0; _i < 2; ++_i) \
;         __builtin_amdgcn_global_load_lds((const unsigned*)((const char*)(gbase) + (voff)[_i]), (LAS unsigned*)(lds + (bufoff) + ldsw + _i * 8192), 16, 0, 0); } while (0)
; #define PG8_LDA(dst, b, h) do { _Pragma("unroll") for (int m = 0; m < 4; ++m) _Pragma("unroll") for (int k = 0; k < 2; ++k) dst[m][k] = *(const LAS bf16x8*)(lds + PG8_SA(b, h) + aoff + m * 2048 + k * 1024); } while (0)
; #define PG8_LDB(dst, b, h) do { _Pragma("unroll") for (int n = 0; n < 2; ++n) _Pragma("unroll") for (int k = 0; k < 2; ++k) dst[n][k] = *(const LAS bf16x8*)(lds + PG8_SB(b, h) + boff + n * 2048 + k * 1024); } while (0)
; #define PG8_MMA(ai, bj, At, Bt) do { __builtin_amdgcn_s_setprio(1); _Pragma("unroll") for (int m = 0; m < 4; ++m) _Pragma("unroll") for (int n = 0; n < 2; ++n) _Pragma("unroll") for (int k = 0; k < 2; ++k) \
;         acc[ai][bj][m][n] = __builtin_amdgcn_mfma_f32_16x16x32_bf16(Bt[n][k], At[m][k], acc[ai][bj][m][n], 0, 0, 0); __builtin_amdgcn_s_setprio(0); } while (0)
; #define PG8_WAIT_L(n) asm volatile("s_waitcnt lgkmcnt(" #n ")" ::: "memory")
; #define PG8_BAR __builtin_amdgcn_s_barrier()
; #define PG8_SCHED __builtin_amdgcn_sched_barrier(0)
; template <class Epi>
; DI void gemm_phase(LAS unsigned char* lds, const Gemm g, const StaticOrder& S, const Epi& E) {
;     ...
;         for (int t = 0; t < nt; t += 2) {
;             const bool last = (t == nt - 2);
;             const char* a1 = cA + (size_t)(t + 1) * kstep;
;             const char* a2 = last ? nA : cA + (size_t)(t + 2) * kstep; const char* b2 = last ? nB : cB + (size_t)(t + 2) * kstep;
;             const char* a3 = a2 + kstep; const char* b3 = b2 + kstep;
;             PG8_LDB(B0, 0, 0); PG8_SCHED; PG8_LDA(At, 0, 0); PG8_STAGE(PG8_SA(1, 1), a1 + hstep, voffA);
;             PG8_WAIT_L(8); PG8_BAR; PG8_WAIT_L(0); PG8_MMA(0, 0, At, B0); PG8_BAR; PG8_SCHED;
;             PG8_LDB(B1, 0, 1); PG8_STAGE(PG8_SB(0, 0), b2, voffB);
;             PG8_BAR; PG8_WAIT_L(0); PG8_MMA(0, 1, At, B1); PG8_BAR;
;             PG8_LDA(At, 0, 1); PG8_STAGE(PG8_SA(0, 0), a2, voffA);
;             PG8_BAR; PG8_WAIT_L(0); PG8_MMA(1, 0, At, B0); PG8_BAR; PG8_SCHED;
.LBB0_723:
	s_ashr_i32 s39, s38, 31
	v_cmp_lt_i64_e32 vcc, s[40:41], v[156:157]
	s_lshl_b64 s[40:41], s[38:39], 19
	s_add_u32 s40, s54, s40
	s_addc_u32 s41, s55, s41
	s_and_b64 s[42:43], vcc, exec
	s_cselect_b32 s39, s41, s47
	s_cselect_b32 s73, s40, s46
	s_ashr_i32 s25, s24, 31
	s_lshl_b64 s[42:43], s[24:25], 19
	s_add_u32 s42, s56, s42
	s_addc_u32 s43, s57, s43
	s_and_b64 s[50:51], vcc, exec
	s_cselect_b32 s25, s43, s49
	s_cselect_b32 s74, s42, s48
	s_add_u32 s46, s46, 0x40080
	s_addc_u32 s47, s47, 0
	s_add_u32 s75, s48, 0x100
	s_addc_u32 s76, s49, 0
	s_mov_b32 s77, -2
	ds_read_b128 v[128:131], v165
	ds_read_b128 v[132:135], v165 offset:1024
	ds_read_b128 v[136:139], v165 offset:2048
	ds_read_b128 v[140:143], v165 offset:3072
	s_add_u32 s48, s46, 0xfffc0080
	s_addc_u32 s49, s47, -1
	s_cmp_eq_u32 s77, 12
	s_cselect_b32 s51, s39, s49
	s_cselect_b32 s50, s73, s48
	s_cselect_b32 s49, s25, s76
	s_cselect_b32 s48, s74, s75
	v_lshl_add_u64 v[160:161], s[46:47], 0, v[152:153]
	s_add_i32 m0, s45, 0xc000
	ds_read_b128 v[168:171], v166
	ds_read_b128 v[172:175], v166 offset:1024
	ds_read_b128 v[176:179], v166 offset:2048
	ds_read_b128 v[182:185], v166 offset:3072
	ds_read_b128 v[186:189], v166 offset:4096
	ds_read_b128 v[190:193], v166 offset:5120
	ds_read_b128 v[194:197], v166 offset:6144
	ds_read_b128 v[198:201], v166 offset:7168
	global_load_lds_dwordx4 v[160:161], off
	v_lshl_add_u64 v[160:161], s[46:47], 0, v[154:155]
	s_add_i32 m0, s45, 0xe000
	s_nop 0
	global_load_lds_dwordx4 v[160:161], off
	s_waitcnt lgkmcnt(8)
	s_barrier
	s_waitcnt lgkmcnt(0)
	s_waitcnt lgkmcnt(0)
	v_mfma_f32_16x16x32_bf16 v[124:127], v[128:131], v[168:171], 0
	v_mfma_f32_16x16x32_bf16 v[120:123], v[136:139], v[168:171], 0
	v_mfma_f32_16x16x32_bf16 v[108:111], v[128:131], v[176:179], 0
	v_mfma_f32_16x16x32_bf16 v[104:107], v[136:139], v[176:179], 0
	v_mfma_f32_16x16x32_bf16 v[92:95], v[128:131], v[186:189], 0
	v_mfma_f32_16x16x32_bf16 v[88:91], v[136:139], v[186:189], 0
	v_mfma_f32_16x16x32_bf16 v[76:79], v[128:131], v[194:197], 0
	v_mfma_f32_16x16x32_bf16 v[72:75], v[136:139], v[194:197], 0
	v_mfma_f32_16x16x32_bf16 v[124:127], v[132:135], v[172:175], v[124:127]
	v_mfma_f32_16x16x32_bf16 v[120:123], v[140:143], v[172:175], v[120:123]
	v_mfma_f32_16x16x32_bf16 v[108:111], v[132:135], v[182:185], v[108:111]
	v_mfma_f32_16x16x32_bf16 v[104:107], v[140:143], v[182:185], v[104:107]
	v_mfma_f32_16x16x32_bf16 v[92:95], v[132:135], v[190:193], v[92:95]
	v_mfma_f32_16x16x32_bf16 v[88:91], v[140:143], v[190:193], v[88:91]
	v_mfma_f32_16x16x32_bf16 v[76:79], v[132:135], v[198:201], v[76:79]
	v_mfma_f32_16x16x32_bf16 v[72:75], v[140:143], v[198:201], v[72:75]
	s_barrier
	s_add_i32 s78, s70, s58
	v_lshl_add_u64 v[160:161], s[48:49], 0, v[146:147]
	s_mov_b32 m0, s78
	ds_read_b128 v[202:205], v167
	ds_read_b128 v[206:209], v167 offset:1024
	ds_read_b128 v[210:213], v167 offset:2048
	ds_read_b128 v[214:217], v167 offset:3072
	global_load_lds_dwordx4 v[160:161], off
	v_lshl_add_u64 v[218:219], s[48:49], 0, v[150:151]
	s_add_i32 m0, s78, 0x2000
	s_nop 0
	global_load_lds_dwordx4 v[218:219], off
	s_barrier
	s_waitcnt lgkmcnt(0)
	s_waitcnt lgkmcnt(0)
	v_mfma_f32_16x16x32_bf16 v[116:119], v[202:205], v[168:171], 0
	v_mfma_f32_16x16x32_bf16 v[112:115], v[210:213], v[168:171], 0
	v_mfma_f32_16x16x32_bf16 v[100:103], v[202:205], v[176:179], 0
	v_mfma_f32_16x16x32_bf16 v[96:99], v[210:213], v[176:179], 0
	v_mfma_f32_16x16x32_bf16 v[84:87], v[202:205], v[186:189], 0
	v_mfma_f32_16x16x32_bf16 v[80:83], v[210:213], v[186:189], 0
	v_mfma_f32_16x16x32_bf16 v[68:71], v[202:205], v[194:197], 0
	v_mfma_f32_16x16x32_bf16 v[64:67], v[210:213], v[194:197], 0
	v_mfma_f32_16x16x32_bf16 v[116:119], v[206:209], v[172:175], v[116:119]
	v_mfma_f32_16x16x32_bf16 v[112:115], v[214:217], v[172:175], v[112:115]
	v_mfma_f32_16x16x32_bf16 v[100:103], v[206:209], v[182:185], v[100:103]
	v_mfma_f32_16x16x32_bf16 v[96:99], v[214:217], v[182:185], v[96:99]
	v_mfma_f32_16x16x32_bf16 v[84:87], v[206:209], v[190:193], v[84:87]
	v_mfma_f32_16x16x32_bf16 v[80:83], v[214:217], v[190:193], v[80:83]
	v_mfma_f32_16x16x32_bf16 v[68:71], v[206:209], v[198:201], v[68:71]
	v_mfma_f32_16x16x32_bf16 v[64:67], v[214:217], v[198:201], v[64:67]
	s_mov_b32 m0, s45
	v_lshl_add_u64 v[220:221], s[50:51], 0, v[144:145]
	s_barrier
	ds_read_b128 v[168:171], v166 offset:16384
	ds_read_b128 v[172:175], v166 offset:17408
	ds_read_b128 v[176:179], v166 offset:18432
	ds_read_b128 v[182:185], v166 offset:19456
	ds_read_b128 v[186:189], v166 offset:20480
	ds_read_b128 v[190:193], v166 offset:21504
	ds_read_b128 v[194:197], v166 offset:22528
	ds_read_b128 v[198:201], v166 offset:23552
	global_load_lds_dwordx4 v[220:221], off
	v_lshl_add_u64 v[222:223], s[50:51], 0, v[148:149]
	s_mov_b32 m0, s59
	s_nop 0
	global_load_lds_dwordx4 v[222:223], off
	s_barrier
	s_waitcnt lgkmcnt(0)
	s_waitcnt lgkmcnt(0)
	v_mfma_f32_16x16x32_bf16 v[60:63], v[128:131], v[168:171], 0
	v_mfma_f32_16x16x32_bf16 v[56:59], v[136:139], v[168:171], 0
	v_mfma_f32_16x16x32_bf16 v[44:47], v[128:131], v[176:179], 0
	v_mfma_f32_16x16x32_bf16 v[40:43], v[136:139], v[176:179], 0
	v_mfma_f32_16x16x32_bf16 v[28:31], v[128:131], v[186:189], 0
	v_mfma_f32_16x16x32_bf16 v[24:27], v[136:139], v[186:189], 0
	v_mfma_f32_16x16x32_bf16 v[12:15], v[128:131], v[194:197], 0
	v_mfma_f32_16x16x32_bf16 v[8:11], v[136:139], v[194:197], 0
	v_mfma_f32_16x16x32_bf16 v[60:63], v[132:135], v[172:175], v[60:63]
	v_mfma_f32_16x16x32_bf16 v[56:59], v[140:143], v[172:175], v[56:59]
	v_mfma_f32_16x16x32_bf16 v[44:47], v[132:135], v[182:185], v[44:47]
	v_mfma_f32_16x16x32_bf16 v[40:43], v[140:143], v[182:185], v[40:43]
	v_mfma_f32_16x16x32_bf16 v[28:31], v[132:135], v[190:193], v[28:31]
	v_mfma_f32_16x16x32_bf16 v[24:27], v[140:143], v[190:193], v[24:27]
	v_mfma_f32_16x16x32_bf16 v[12:15], v[132:135], v[198:201], v[12:15]
	v_mfma_f32_16x16x32_bf16 v[8:11], v[140:143], v[198:201], v[8:11]
	s_barrier
; #define PG8_STAGE(bufoff, gbase, voff) do { _Pragma("unroll") for (int _i = 0; _i < 2; ++_i) \
;         __builtin_amdgcn_global_load_lds((const unsigned*)((const char*)(gbase) + (voff)[_i]), (LAS unsigned*)(lds + (bufoff) + ldsw + _i * 8192), 16, 0, 0); } while (0)
; #define PG8_LDA(dst, b, h) do { _Pragma("unroll") for (int m = 0; m < 4; ++m) _Pragma("unroll") for (int k = 0; k < 2; ++k) dst[m][k] = *(const LAS bf16x8*)(lds + PG8_SA(b, h) + aoff + m * 2048 + k * 1024); } while (0)
; #define PG8_LDB(dst, b, h) do { _Pragma("unroll") for (int n = 0; n < 2; ++n) _Pragma("unroll") for (int k = 0; k < 2; ++k) dst[n][k] = *(const LAS bf16x8*)(lds + PG8_SB(b, h) + boff + n * 2048 + k * 1024); } while (0)
; #define PG8_MMA(ai, bj, At, Bt) do { __builtin_amdgcn_s_setprio(1); _Pragma("unroll") for (int m = 0; m < 4; ++m) _Pragma("unroll") for (int n = 0; n < 2; ++n) _Pragma("unroll") for (int k = 0; k < 2; ++k) \
;         acc[ai][bj][m][n] = __builtin_amdgcn_mfma_f32_16x16x32_bf16(Bt[n][k], At[m][k], acc[ai][bj][m][n], 0, 0, 0); __builtin_amdgcn_s_setprio(0); } while (0)
; #define PG8_WAIT_V(n) asm volatile("s_waitcnt vmcnt(" #n ")" ::: "memory")
; #define PG8_WAIT_L(n) asm volatile("s_waitcnt lgkmcnt(" #n ")" ::: "memory")
; #define PG8_BAR __builtin_amdgcn_s_barrier()
; #define PG8_SCHED __builtin_amdgcn_sched_barrier(0)
; template <class Epi>
; DI void gemm_phase(LAS unsigned char* lds, const Gemm g, const StaticOrder& S, const Epi& E) {
;     ...
;             PG8_STAGE(PG8_SB(0, 1), b2 + hstep, voffB);
;             PG8_WAIT_V(6); PG8_BAR; PG8_MMA(1, 1, At, B1); PG8_BAR;
;             PG8_LDB(B0, 1, 0); PG8_SCHED; PG8_LDA(At, 1, 0); PG8_STAGE(PG8_SA(0, 1), a2 + hstep, voffA);
;             PG8_WAIT_L(8); PG8_BAR; PG8_WAIT_L(0); PG8_MMA(0, 0, At, B0); PG8_BAR; PG8_SCHED;
;             PG8_LDB(B1, 1, 1); PG8_STAGE(PG8_SB(1, 0), b3, voffB);
	s_add_u32 s78, s48, 0x40000
	s_addc_u32 s79, s49, 0
	s_add_i32 s80, s71, s58
	v_lshl_add_u64 v[128:129], s[78:79], 0, v[146:147]
	s_mov_b32 m0, s80
	s_nop 0
	global_load_lds_dwordx4 v[128:129], off
	v_lshl_add_u64 v[128:129], s[78:79], 0, v[150:151]
	s_add_i32 m0, s80, 0x2000
	s_nop 0
	global_load_lds_dwordx4 v[128:129], off
	s_lshl_b32 s84, s44, 20
	s_lshl_b32 s85, s72, 10
	s_add_u32 s84, s84, s85
	s_add_i32 s85, s77, 2
	s_lshl_b32 s85, s85, 13
	s_add_u32 s84, s84, s85
	s_add_u32 s84, s36, s84
	s_addc_u32 s85, s37, 0
	s_waitcnt vmcnt(6)
	global_load_dword v249, v248, s[84:85]
	s_barrier
	v_mfma_f32_16x16x32_bf16 v[52:55], v[202:205], v[168:171], 0
	v_mfma_f32_16x16x32_bf16 v[48:51], v[210:213], v[168:171], 0
	v_mfma_f32_16x16x32_bf16 v[36:39], v[202:205], v[176:179], 0
	v_mfma_f32_16x16x32_bf16 v[32:35], v[210:213], v[176:179], 0
	v_mfma_f32_16x16x32_bf16 v[20:23], v[202:205], v[186:189], 0
	v_mfma_f32_16x16x32_bf16 v[16:19], v[210:213], v[186:189], 0
	v_mfma_f32_16x16x32_bf16 v[4:7], v[202:205], v[194:197], 0
	v_mfma_f32_16x16x32_bf16 v[0:3], v[210:213], v[194:197], 0
	v_mfma_f32_16x16x32_bf16 v[52:55], v[206:209], v[172:175], v[52:55]
	v_mfma_f32_16x16x32_bf16 v[48:51], v[214:217], v[172:175], v[48:51]
	v_mfma_f32_16x16x32_bf16 v[36:39], v[206:209], v[182:185], v[36:39]
	v_mfma_f32_16x16x32_bf16 v[32:35], v[214:217], v[182:185], v[32:35]
	v_mfma_f32_16x16x32_bf16 v[20:23], v[206:209], v[190:193], v[20:23]
	v_mfma_f32_16x16x32_bf16 v[16:19], v[214:217], v[190:193], v[16:19]
	v_mfma_f32_16x16x32_bf16 v[4:7], v[206:209], v[198:201], v[4:7]
	v_mfma_f32_16x16x32_bf16 v[0:3], v[214:217], v[198:201], v[0:3]
	s_add_i32 s78, 0, 0x18000
	v_add_u32_e32 v140, s78, v163
	s_barrier
	ds_read_b128 v[128:131], v140
	ds_read_b128 v[132:135], v140 offset:1024
	ds_read_b128 v[136:139], v140 offset:2048
	ds_read_b128 v[140:143], v140 offset:3072
	s_add_u32 s50, s50, 0x40000
	s_addc_u32 s51, s51, 0
	s_mov_b32 m0, s60
	v_lshl_add_u64 v[202:203], s[50:51], 0, v[144:145]
	ds_read_b128 v[168:171], v166 offset:32768
	ds_read_b128 v[172:175], v166 offset:33792
	ds_read_b128 v[176:179], v166 offset:34816
	ds_read_b128 v[182:185], v166 offset:35840
	ds_read_b128 v[186:189], v166 offset:36864
	ds_read_b128 v[190:193], v166 offset:37888
	ds_read_b128 v[194:197], v166 offset:38912
	ds_read_b128 v[198:201], v166 offset:39936
	global_load_lds_dwordx4 v[202:203], off
	v_lshl_add_u64 v[202:203], s[50:51], 0, v[148:149]
	s_mov_b32 m0, s61
	s_nop 0
	global_load_lds_dwordx4 v[202:203], off
	s_waitcnt lgkmcnt(8)
	s_barrier
	s_waitcnt lgkmcnt(0)
	s_waitcnt lgkmcnt(0)
	v_mfma_f32_16x16x32_bf16 v[124:127], v[128:131], v[168:171], v[124:127]
	v_mfma_f32_16x16x32_bf16 v[120:123], v[136:139], v[168:171], v[120:123]
	v_mfma_f32_16x16x32_bf16 v[108:111], v[128:131], v[176:179], v[108:111]
	v_mfma_f32_16x16x32_bf16 v[104:107], v[136:139], v[176:179], v[104:107]
	v_mfma_f32_16x16x32_bf16 v[92:95], v[128:131], v[186:189], v[92:95]
	v_mfma_f32_16x16x32_bf16 v[88:91], v[136:139], v[186:189], v[88:91]
	v_mfma_f32_16x16x32_bf16 v[76:79], v[128:131], v[194:197], v[76:79]
	v_mfma_f32_16x16x32_bf16 v[72:75], v[136:139], v[194:197], v[72:75]
	v_mfma_f32_16x16x32_bf16 v[124:127], v[132:135], v[172:175], v[124:127]
	v_mfma_f32_16x16x32_bf16 v[120:123], v[140:143], v[172:175], v[120:123]
	v_mfma_f32_16x16x32_bf16 v[108:111], v[132:135], v[182:185], v[108:111]
	v_mfma_f32_16x16x32_bf16 v[104:107], v[140:143], v[182:185], v[104:107]
	v_mfma_f32_16x16x32_bf16 v[92:95], v[132:135], v[190:193], v[92:95]
	v_mfma_f32_16x16x32_bf16 v[88:91], v[140:143], v[190:193], v[88:91]
	v_mfma_f32_16x16x32_bf16 v[76:79], v[132:135], v[198:201], v[76:79]
	v_mfma_f32_16x16x32_bf16 v[72:75], v[140:143], v[198:201], v[72:75]
	s_barrier
	s_add_i32 s50, 0, 0x1c000
	s_add_i32 s51, s78, s58
	v_add_u32_e32 v214, s50, v163
	v_lshl_add_u64 v[160:161], v[160:161], 0, s[12:13]
	s_mov_b32 m0, s51
	ds_read_b128 v[202:205], v214
	ds_read_b128 v[206:209], v214 offset:1024
	ds_read_b128 v[210:213], v214 offset:2048
	ds_read_b128 v[214:217], v214 offset:3072
	global_load_lds_dwordx4 v[160:161], off
	v_lshl_add_u64 v[160:161], v[218:219], 0, s[12:13]
	s_add_i32 m0, s51, 0x2000
	s_nop 0
	global_load_lds_dwordx4 v[160:161], off
	s_barrier
; #define PG8_STAGE(bufoff, gbase, voff) do { _Pragma("unroll") for (int _i = 0; _i < 2; ++_i) \
;         __builtin_amdgcn_global_load_lds((const unsigned*)((const char*)(gbase) + (voff)[_i]), (LAS unsigned*)(lds + (bufoff) + ldsw + _i * 8192), 16, 0, 0); } while (0)
; #define PG8_LDA(dst, b, h) do { _Pragma("unroll") for (int m = 0; m < 4; ++m) _Pragma("unroll") for (int k = 0; k < 2; ++k) dst[m][k] = *(const LAS bf16x8*)(lds + PG8_SA(b, h) + aoff + m * 2048 + k * 1024); } while (0)
; #define PG8_MMA(ai, bj, At, Bt) do { __builtin_amdgcn_s_setprio(1); _Pragma("unroll") for (int m = 0; m < 4; ++m) _Pragma("unroll") for (int n = 0; n < 2; ++n) _Pragma("unroll") for (int k = 0; k < 2; ++k) \
;         acc[ai][bj][m][n] = __builtin_amdgcn_mfma_f32_16x16x32_bf16(Bt[n][k], At[m][k], acc[ai][bj][m][n], 0, 0, 0); __builtin_amdgcn_s_setprio(0); } while (0)
; #define PG8_WAIT_V(n) asm volatile("s_waitcnt vmcnt(" #n ")" ::: "memory")
; #define PG8_WAIT_L(n) asm volatile("s_waitcnt lgkmcnt(" #n ")" ::: "memory")
; #define PG8_BAR __builtin_amdgcn_s_barrier()
; #define PG8_SCHED __builtin_amdgcn_sched_barrier(0)
; template <class Epi>
; DI void gemm_phase(LAS unsigned char* lds, const Gemm g, const StaticOrder& S, const Epi& E) {
;     ...
;             PG8_BAR; PG8_WAIT_L(0); PG8_MMA(0, 1, At, B1); PG8_BAR;
;             PG8_LDA(At, 1, 1); PG8_STAGE(PG8_SA(1, 0), a3, voffA);
;             PG8_BAR; PG8_WAIT_L(0); PG8_MMA(1, 0, At, B0); PG8_BAR; PG8_SCHED;
;             PG8_STAGE(PG8_SB(1, 1), b3 + hstep, voffB);
;             PG8_WAIT_V(6); PG8_BAR; PG8_MMA(1, 1, At, B1); PG8_BAR;
;         }
	s_waitcnt lgkmcnt(0)
	s_waitcnt lgkmcnt(0)
	v_mfma_f32_16x16x32_bf16 v[116:119], v[202:205], v[168:171], v[116:119]
	v_mfma_f32_16x16x32_bf16 v[112:115], v[210:213], v[168:171], v[112:115]
	v_mfma_f32_16x16x32_bf16 v[100:103], v[202:205], v[176:179], v[100:103]
	v_mfma_f32_16x16x32_bf16 v[96:99], v[210:213], v[176:179], v[96:99]
	v_mfma_f32_16x16x32_bf16 v[84:87], v[202:205], v[186:189], v[84:87]
	v_mfma_f32_16x16x32_bf16 v[80:83], v[210:213], v[186:189], v[80:83]
	v_mfma_f32_16x16x32_bf16 v[68:71], v[202:205], v[194:197], v[68:71]
	v_mfma_f32_16x16x32_bf16 v[64:67], v[210:213], v[194:197], v[64:67]
	v_mfma_f32_16x16x32_bf16 v[116:119], v[206:209], v[172:175], v[116:119]
	v_mfma_f32_16x16x32_bf16 v[112:115], v[214:217], v[172:175], v[112:115]
	v_mfma_f32_16x16x32_bf16 v[100:103], v[206:209], v[182:185], v[100:103]
	v_mfma_f32_16x16x32_bf16 v[96:99], v[214:217], v[182:185], v[96:99]
	v_mfma_f32_16x16x32_bf16 v[84:87], v[206:209], v[190:193], v[84:87]
	v_mfma_f32_16x16x32_bf16 v[80:83], v[214:217], v[190:193], v[80:83]
	v_mfma_f32_16x16x32_bf16 v[68:71], v[206:209], v[198:201], v[68:71]
	v_mfma_f32_16x16x32_bf16 v[64:67], v[214:217], v[198:201], v[64:67]
	s_mov_b32 m0, s65
	v_lshl_add_u64 v[160:161], v[220:221], 0, s[12:13]
	s_barrier
	ds_read_b128 v[168:171], v166 offset:49152
	ds_read_b128 v[172:175], v166 offset:50176
	ds_read_b128 v[176:179], v166 offset:51200
	ds_read_b128 v[182:185], v166 offset:52224
	ds_read_b128 v[186:189], v166 offset:53248
	ds_read_b128 v[190:193], v166 offset:54272
	ds_read_b128 v[194:197], v166 offset:55296
	ds_read_b128 v[198:201], v166 offset:56320
	global_load_lds_dwordx4 v[160:161], off
	v_lshl_add_u64 v[160:161], v[222:223], 0, s[12:13]
	s_mov_b32 m0, s66
	s_nop 0
	global_load_lds_dwordx4 v[160:161], off
	s_barrier
	s_waitcnt lgkmcnt(0)
	s_waitcnt lgkmcnt(0)
	v_mfma_f32_16x16x32_bf16 v[60:63], v[128:131], v[168:171], v[60:63]
	v_mfma_f32_16x16x32_bf16 v[56:59], v[136:139], v[168:171], v[56:59]
	v_mfma_f32_16x16x32_bf16 v[44:47], v[128:131], v[176:179], v[44:47]
	v_mfma_f32_16x16x32_bf16 v[40:43], v[136:139], v[176:179], v[40:43]
	v_mfma_f32_16x16x32_bf16 v[28:31], v[128:131], v[186:189], v[28:31]
	v_mfma_f32_16x16x32_bf16 v[24:27], v[136:139], v[186:189], v[24:27]
	v_mfma_f32_16x16x32_bf16 v[12:15], v[128:131], v[194:197], v[12:15]
	v_mfma_f32_16x16x32_bf16 v[8:11], v[136:139], v[194:197], v[8:11]
	v_mfma_f32_16x16x32_bf16 v[60:63], v[132:135], v[172:175], v[60:63]
	v_mfma_f32_16x16x32_bf16 v[56:59], v[140:143], v[172:175], v[56:59]
	v_mfma_f32_16x16x32_bf16 v[44:47], v[132:135], v[182:185], v[44:47]
	v_mfma_f32_16x16x32_bf16 v[40:43], v[140:143], v[182:185], v[40:43]
	v_mfma_f32_16x16x32_bf16 v[28:31], v[132:135], v[190:193], v[28:31]
	v_mfma_f32_16x16x32_bf16 v[24:27], v[140:143], v[190:193], v[24:27]
	v_mfma_f32_16x16x32_bf16 v[12:15], v[132:135], v[198:201], v[12:15]
	v_mfma_f32_16x16x32_bf16 v[8:11], v[140:143], v[198:201], v[8:11]
	s_barrier
	s_add_u32 s48, s48, 0x40080
	s_addc_u32 s49, s49, 0
	s_add_i32 s50, s50, s58
	v_lshl_add_u64 v[128:129], s[48:49], 0, v[146:147]
	s_mov_b32 m0, s50
	s_nop 0
	global_load_lds_dwordx4 v[128:129], off
	v_lshl_add_u64 v[128:129], s[48:49], 0, v[150:151]
	s_add_i32 m0, s50, 0x2000
	s_nop 0
	global_load_lds_dwordx4 v[128:129], off
	s_waitcnt vmcnt(6)
	s_barrier
	v_mfma_f32_16x16x32_bf16 v[52:55], v[202:205], v[168:171], v[52:55]
	v_mfma_f32_16x16x32_bf16 v[48:51], v[210:213], v[168:171], v[48:51]
	v_mfma_f32_16x16x32_bf16 v[36:39], v[202:205], v[176:179], v[36:39]
	v_mfma_f32_16x16x32_bf16 v[32:35], v[210:213], v[176:179], v[32:35]
	v_mfma_f32_16x16x32_bf16 v[20:23], v[202:205], v[186:189], v[20:23]
	v_mfma_f32_16x16x32_bf16 v[16:19], v[210:213], v[186:189], v[16:19]
	v_mfma_f32_16x16x32_bf16 v[4:7], v[202:205], v[194:197], v[4:7]
	v_mfma_f32_16x16x32_bf16 v[0:3], v[210:213], v[194:197], v[0:3]
	v_mfma_f32_16x16x32_bf16 v[52:55], v[206:209], v[172:175], v[52:55]
	v_mfma_f32_16x16x32_bf16 v[48:51], v[214:217], v[172:175], v[48:51]
	v_mfma_f32_16x16x32_bf16 v[36:39], v[206:209], v[182:185], v[36:39]
	v_mfma_f32_16x16x32_bf16 v[32:35], v[214:217], v[182:185], v[32:35]
	v_mfma_f32_16x16x32_bf16 v[20:23], v[206:209], v[190:193], v[20:23]
	v_mfma_f32_16x16x32_bf16 v[16:19], v[214:217], v[190:193], v[16:19]
	v_mfma_f32_16x16x32_bf16 v[4:7], v[206:209], v[198:201], v[4:7]
	v_mfma_f32_16x16x32_bf16 v[0:3], v[214:217], v[198:201], v[0:3]
	s_add_i32 s77, s77, 2
	s_add_u32 s46, s46, 0x100
	s_addc_u32 s47, s47, 0
	s_add_u32 s75, s75, 0x100
	s_addc_u32 s76, s76, 0
	s_cmp_gt_u32 s77, 13
	s_barrier

; #define PG8_STAGE(bufoff, gbase, voff) do { _Pragma("unroll") for (int _i = 0; _i < 2; ++_i) \
;         __builtin_amdgcn_global_load_lds((const unsigned*)((const char*)(gbase) + (voff)[_i]), (LAS unsigned*)(lds + (bufoff) + ldsw + _i * 8192), 16, 0, 0); } while (0)
; #define PG8_LDA(dst, b, h) do { _Pragma("unroll") for (int m = 0; m < 4; ++m) _Pragma("unroll") for (int k = 0; k < 2; ++k) dst[m][k] = *(const LAS bf16x8*)(lds + PG8_SA(b, h) + aoff + m * 2048 + k * 1024); } while (0)
; #define PG8_LDB(dst, b, h) do { _Pragma("unroll") for (int n = 0; n < 2; ++n) _Pragma("unroll") for (int k = 0; k < 2; ++k) dst[n][k] = *(const LAS bf16x8*)(lds + PG8_SB(b, h) + boff + n * 2048 + k * 1024); } while (0)
; #define PG8_MMA(ai, bj, At, Bt) do { __builtin_amdgcn_s_setprio(1); _Pragma("unroll") for (int m = 0; m < 4; ++m) _Pragma("unroll") for (int n = 0; n < 2; ++n) _Pragma("unroll") for (int k = 0; k < 2; ++k) \
;         acc[ai][bj][m][n] = __builtin_amdgcn_mfma_f32_16x16x32_bf16(Bt[n][k], At[m][k], acc[ai][bj][m][n], 0, 0, 0); __builtin_amdgcn_s_setprio(0); } while (0)
; #define PG8_WAIT_L(n) asm volatile("s_waitcnt lgkmcnt(" #n ")" ::: "memory")
; #define PG8_BAR __builtin_amdgcn_s_barrier()
; #define PG8_SCHED __builtin_amdgcn_sched_barrier(0)
; template <class Epi>
; DI void gemm_phase(LAS unsigned char* lds, const Gemm g, const StaticOrder& S, const Epi& E) {
;     ...
;         for (int t = 0; t < nt; t += 2) {
;             const bool last = (t == nt - 2);
;             const char* a1 = cA + (size_t)(t + 1) * kstep;
;             const char* a2 = last ? nA : cA + (size_t)(t + 2) * kstep; const char* b2 = last ? nB : cB + (size_t)(t + 2) * kstep;
;             const char* a3 = a2 + kstep; const char* b3 = b2 + kstep;
;             PG8_LDB(B0, 0, 0); PG8_SCHED; PG8_LDA(At, 0, 0); PG8_STAGE(PG8_SA(1, 1), a1 + hstep, voffA);
;             PG8_WAIT_L(8); PG8_BAR; PG8_WAIT_L(0); PG8_MMA(0, 0, At, B0); PG8_BAR; PG8_SCHED;
;             PG8_LDB(B1, 0, 1); PG8_STAGE(PG8_SB(0, 0), b2, voffB);
;             PG8_BAR; PG8_WAIT_L(0); PG8_MMA(0, 1, At, B1); PG8_BAR;
;             PG8_LDA(At, 0, 1); PG8_STAGE(PG8_SA(0, 0), a2, voffA);
;             PG8_BAR; PG8_WAIT_L(0); PG8_MMA(1, 0, At, B0); PG8_BAR; PG8_SCHED;
.LBB0_848:
	s_ashr_i32 s17, s16, 31
	v_cmp_lt_i64_e32 vcc, s[18:19], v[140:141]
	s_lshl_b64 s[18:19], s[16:17], 19
	s_add_u32 s18, s41, s18
	s_addc_u32 s19, s42, s19
	s_and_b64 s[20:21], vcc, exec
	s_cselect_b32 s17, s19, s25
	s_cselect_b32 s59, s18, s24
	s_ashr_i32 s15, s14, 31
	s_lshl_b64 s[20:21], s[14:15], 19
	s_add_u32 s20, s43, s20
	s_addc_u32 s21, s44, s21
	s_and_b64 s[38:39], vcc, exec
	s_cselect_b32 s15, s21, s37
	s_cselect_b32 s60, s20, s36
	s_add_u32 s24, s24, 0x40080
	s_addc_u32 s25, s25, 0
	s_add_u32 s61, s36, 0x100
	s_addc_u32 s62, s37, 0
	s_mov_b32 s63, -2
	ds_read_b128 v[152:155], v149
	ds_read_b128 v[156:159], v149 offset:1024
	ds_read_b128 v[160:163], v149 offset:2048
	ds_read_b128 v[164:167], v149 offset:3072
	s_add_u32 s36, s24, 0xfffc0080
	s_addc_u32 s37, s25, -1
	s_cmp_eq_u32 s63, 12
	s_cselect_b32 s39, s17, s37
	s_cselect_b32 s38, s59, s36
	s_cselect_b32 s37, s15, s62
	s_cselect_b32 s36, s60, s61
	v_lshl_add_u64 v[144:145], s[24:25], 0, v[136:137]
	s_add_i32 m0, s23, 0xc000
	ds_read_b128 v[168:171], v150
	ds_read_b128 v[172:175], v150 offset:1024
	ds_read_b128 v[176:179], v150 offset:2048
	ds_read_b128 v[182:185], v150 offset:3072
	ds_read_b128 v[186:189], v150 offset:4096
	ds_read_b128 v[190:193], v150 offset:5120
	ds_read_b128 v[194:197], v150 offset:6144
	ds_read_b128 v[198:201], v150 offset:7168
	global_load_lds_dwordx4 v[144:145], off
	v_lshl_add_u64 v[144:145], s[24:25], 0, v[138:139]
	s_add_i32 m0, s23, 0xe000
	s_nop 0
	global_load_lds_dwordx4 v[144:145], off
	s_waitcnt lgkmcnt(8)
	s_barrier
	s_waitcnt lgkmcnt(0)
	s_waitcnt lgkmcnt(0)
	v_mfma_f32_16x16x32_bf16 v[124:127], v[152:155], v[168:171], 0
	v_mfma_f32_16x16x32_bf16 v[120:123], v[160:163], v[168:171], 0
	v_mfma_f32_16x16x32_bf16 v[108:111], v[152:155], v[176:179], 0
	v_mfma_f32_16x16x32_bf16 v[104:107], v[160:163], v[176:179], 0
	v_mfma_f32_16x16x32_bf16 v[92:95], v[152:155], v[186:189], 0
	v_mfma_f32_16x16x32_bf16 v[88:91], v[160:163], v[186:189], 0
	v_mfma_f32_16x16x32_bf16 v[76:79], v[152:155], v[194:197], 0
	v_mfma_f32_16x16x32_bf16 v[72:75], v[160:163], v[194:197], 0
	v_mfma_f32_16x16x32_bf16 v[124:127], v[156:159], v[172:175], v[124:127]
	v_mfma_f32_16x16x32_bf16 v[120:123], v[164:167], v[172:175], v[120:123]
	v_mfma_f32_16x16x32_bf16 v[108:111], v[156:159], v[182:185], v[108:111]
	v_mfma_f32_16x16x32_bf16 v[104:107], v[164:167], v[182:185], v[104:107]
	v_mfma_f32_16x16x32_bf16 v[92:95], v[156:159], v[190:193], v[92:95]
	v_mfma_f32_16x16x32_bf16 v[88:91], v[164:167], v[190:193], v[88:91]
	v_mfma_f32_16x16x32_bf16 v[76:79], v[156:159], v[198:201], v[76:79]
	v_mfma_f32_16x16x32_bf16 v[72:75], v[164:167], v[198:201], v[72:75]
	s_barrier
	s_add_i32 s64, s55, s45
	v_lshl_add_u64 v[144:145], s[36:37], 0, v[132:133]
	s_mov_b32 m0, s64
	ds_read_b128 v[202:205], v151
	ds_read_b128 v[206:209], v151 offset:1024
	ds_read_b128 v[210:213], v151 offset:2048
	ds_read_b128 v[214:217], v151 offset:3072
	global_load_lds_dwordx4 v[144:145], off
	v_lshl_add_u64 v[218:219], s[36:37], 0, v[128:129]
	s_add_i32 m0, s64, 0x2000
	s_nop 0
	global_load_lds_dwordx4 v[218:219], off
	s_barrier
	s_waitcnt lgkmcnt(0)
	s_waitcnt lgkmcnt(0)
	v_mfma_f32_16x16x32_bf16 v[116:119], v[202:205], v[168:171], 0
	v_mfma_f32_16x16x32_bf16 v[112:115], v[210:213], v[168:171], 0
	v_mfma_f32_16x16x32_bf16 v[100:103], v[202:205], v[176:179], 0
	v_mfma_f32_16x16x32_bf16 v[96:99], v[210:213], v[176:179], 0
	v_mfma_f32_16x16x32_bf16 v[84:87], v[202:205], v[186:189], 0
	v_mfma_f32_16x16x32_bf16 v[80:83], v[210:213], v[186:189], 0
	v_mfma_f32_16x16x32_bf16 v[68:71], v[202:205], v[194:197], 0
	v_mfma_f32_16x16x32_bf16 v[64:67], v[210:213], v[194:197], 0
	v_mfma_f32_16x16x32_bf16 v[116:119], v[206:209], v[172:175], v[116:119]
	v_mfma_f32_16x16x32_bf16 v[112:115], v[214:217], v[172:175], v[112:115]
	v_mfma_f32_16x16x32_bf16 v[100:103], v[206:209], v[182:185], v[100:103]
	v_mfma_f32_16x16x32_bf16 v[96:99], v[214:217], v[182:185], v[96:99]
	v_mfma_f32_16x16x32_bf16 v[84:87], v[206:209], v[190:193], v[84:87]
	v_mfma_f32_16x16x32_bf16 v[80:83], v[214:217], v[190:193], v[80:83]
	v_mfma_f32_16x16x32_bf16 v[68:71], v[206:209], v[198:201], v[68:71]
	v_mfma_f32_16x16x32_bf16 v[64:67], v[214:217], v[198:201], v[64:67]
	s_mov_b32 m0, s23
	v_lshl_add_u64 v[220:221], s[38:39], 0, v[134:135]
	s_barrier
	ds_read_b128 v[168:171], v150 offset:16384
	ds_read_b128 v[172:175], v150 offset:17408
	ds_read_b128 v[176:179], v150 offset:18432
	ds_read_b128 v[182:185], v150 offset:19456
	ds_read_b128 v[186:189], v150 offset:20480
	ds_read_b128 v[190:193], v150 offset:21504
	ds_read_b128 v[194:197], v150 offset:22528
	ds_read_b128 v[198:201], v150 offset:23552
	global_load_lds_dwordx4 v[220:221], off
	v_lshl_add_u64 v[222:223], s[38:39], 0, v[130:131]
	s_mov_b32 m0, s48
	s_nop 0
	global_load_lds_dwordx4 v[222:223], off
	s_barrier
	s_waitcnt lgkmcnt(0)
	s_waitcnt lgkmcnt(0)
	v_mfma_f32_16x16x32_bf16 v[60:63], v[152:155], v[168:171], 0
	v_mfma_f32_16x16x32_bf16 v[56:59], v[160:163], v[168:171], 0
	v_mfma_f32_16x16x32_bf16 v[44:47], v[152:155], v[176:179], 0
	v_mfma_f32_16x16x32_bf16 v[40:43], v[160:163], v[176:179], 0
	v_mfma_f32_16x16x32_bf16 v[28:31], v[152:155], v[186:189], 0
	v_mfma_f32_16x16x32_bf16 v[24:27], v[160:163], v[186:189], 0
	v_mfma_f32_16x16x32_bf16 v[12:15], v[152:155], v[194:197], 0
	v_mfma_f32_16x16x32_bf16 v[8:11], v[160:163], v[194:197], 0
	v_mfma_f32_16x16x32_bf16 v[60:63], v[156:159], v[172:175], v[60:63]
	v_mfma_f32_16x16x32_bf16 v[56:59], v[164:167], v[172:175], v[56:59]
	v_mfma_f32_16x16x32_bf16 v[44:47], v[156:159], v[182:185], v[44:47]
	v_mfma_f32_16x16x32_bf16 v[40:43], v[164:167], v[182:185], v[40:43]
	v_mfma_f32_16x16x32_bf16 v[28:31], v[156:159], v[190:193], v[28:31]
	v_mfma_f32_16x16x32_bf16 v[24:27], v[164:167], v[190:193], v[24:27]
	v_mfma_f32_16x16x32_bf16 v[12:15], v[156:159], v[198:201], v[12:15]
	v_mfma_f32_16x16x32_bf16 v[8:11], v[164:167], v[198:201], v[8:11]
	s_barrier
; #define PG8_STAGE(bufoff, gbase, voff) do { _Pragma("unroll") for (int _i = 0; _i < 2; ++_i) \
;         __builtin_amdgcn_global_load_lds((const unsigned*)((const char*)(gbase) + (voff)[_i]), (LAS unsigned*)(lds + (bufoff) + ldsw + _i * 8192), 16, 0, 0); } while (0)
; #define PG8_LDA(dst, b, h) do { _Pragma("unroll") for (int m = 0; m < 4; ++m) _Pragma("unroll") for (int k = 0; k < 2; ++k) dst[m][k] = *(const LAS bf16x8*)(lds + PG8_SA(b, h) + aoff + m * 2048 + k * 1024); } while (0)
; #define PG8_LDB(dst, b, h) do { _Pragma("unroll") for (int n = 0; n < 2; ++n) _Pragma("unroll") for (int k = 0; k < 2; ++k) dst[n][k] = *(const LAS bf16x8*)(lds + PG8_SB(b, h) + boff + n * 2048 + k * 1024); } while (0)
; #define PG8_MMA(ai, bj, At, Bt) do { __builtin_amdgcn_s_setprio(1); _Pragma("unroll") for (int m = 0; m < 4; ++m) _Pragma("unroll") for (int n = 0; n < 2; ++n) _Pragma("unroll") for (int k = 0; k < 2; ++k) \
;         acc[ai][bj][m][n] = __builtin_amdgcn_mfma_f32_16x16x32_bf16(Bt[n][k], At[m][k], acc[ai][bj][m][n], 0, 0, 0); __builtin_amdgcn_s_setprio(0); } while (0)
; #define PG8_WAIT_V(n) asm volatile("s_waitcnt vmcnt(" #n ")" ::: "memory")
; #define PG8_WAIT_L(n) asm volatile("s_waitcnt lgkmcnt(" #n ")" ::: "memory")
; #define PG8_BAR __builtin_amdgcn_s_barrier()
; #define PG8_SCHED __builtin_amdgcn_sched_barrier(0)
; template <class Epi>
; DI void gemm_phase(LAS unsigned char* lds, const Gemm g, const StaticOrder& S, const Epi& E) {
;     ...
;             PG8_STAGE(PG8_SB(0, 1), b2 + hstep, voffB);
;             PG8_WAIT_V(6); PG8_BAR; PG8_MMA(1, 1, At, B1); PG8_BAR;
;             PG8_LDB(B0, 1, 0); PG8_SCHED; PG8_LDA(At, 1, 0); PG8_STAGE(PG8_SA(0, 1), a2 + hstep, voffA);
;             PG8_WAIT_L(8); PG8_BAR; PG8_WAIT_L(0); PG8_MMA(0, 0, At, B0); PG8_BAR; PG8_SCHED;
;             PG8_LDB(B1, 1, 1); PG8_STAGE(PG8_SB(1, 0), b3, voffB);
	s_add_u32 s64, s36, 0x40000
	s_addc_u32 s65, s37, 0
	s_add_i32 s66, s56, s45
	v_lshl_add_u64 v[152:153], s[64:65], 0, v[132:133]
	s_mov_b32 m0, s66
	s_nop 0
	global_load_lds_dwordx4 v[152:153], off
	v_lshl_add_u64 v[152:153], s[64:65], 0, v[128:129]
	s_add_i32 m0, s66, 0x2000
	s_nop 0
	global_load_lds_dwordx4 v[152:153], off
	s_waitcnt vmcnt(6)
	s_barrier
	v_mfma_f32_16x16x32_bf16 v[52:55], v[202:205], v[168:171], 0
	v_mfma_f32_16x16x32_bf16 v[48:51], v[210:213], v[168:171], 0
	v_mfma_f32_16x16x32_bf16 v[36:39], v[202:205], v[176:179], 0
	v_mfma_f32_16x16x32_bf16 v[32:35], v[210:213], v[176:179], 0
	v_mfma_f32_16x16x32_bf16 v[20:23], v[202:205], v[186:189], 0
	v_mfma_f32_16x16x32_bf16 v[16:19], v[210:213], v[186:189], 0
	v_mfma_f32_16x16x32_bf16 v[4:7], v[202:205], v[194:197], 0
	v_mfma_f32_16x16x32_bf16 v[0:3], v[210:213], v[194:197], 0
	v_mfma_f32_16x16x32_bf16 v[52:55], v[206:209], v[172:175], v[52:55]
	v_mfma_f32_16x16x32_bf16 v[48:51], v[214:217], v[172:175], v[48:51]
	v_mfma_f32_16x16x32_bf16 v[36:39], v[206:209], v[182:185], v[36:39]
	v_mfma_f32_16x16x32_bf16 v[32:35], v[214:217], v[182:185], v[32:35]
	v_mfma_f32_16x16x32_bf16 v[20:23], v[206:209], v[190:193], v[20:23]
	v_mfma_f32_16x16x32_bf16 v[16:19], v[214:217], v[190:193], v[16:19]
	v_mfma_f32_16x16x32_bf16 v[4:7], v[206:209], v[198:201], v[4:7]
	v_mfma_f32_16x16x32_bf16 v[0:3], v[214:217], v[198:201], v[0:3]
	s_add_i32 s64, 0, 0x18000
	v_add_u32_e32 v164, s64, v147
	s_barrier
	ds_read_b128 v[152:155], v164
	ds_read_b128 v[156:159], v164 offset:1024
	ds_read_b128 v[160:163], v164 offset:2048
	ds_read_b128 v[164:167], v164 offset:3072
	s_add_u32 s38, s38, 0x40000
	s_addc_u32 s39, s39, 0
	s_mov_b32 m0, s49
	v_lshl_add_u64 v[202:203], s[38:39], 0, v[134:135]
	ds_read_b128 v[168:171], v150 offset:32768
	ds_read_b128 v[172:175], v150 offset:33792
	ds_read_b128 v[176:179], v150 offset:34816
	ds_read_b128 v[182:185], v150 offset:35840
	ds_read_b128 v[186:189], v150 offset:36864
	ds_read_b128 v[190:193], v150 offset:37888
	ds_read_b128 v[194:197], v150 offset:38912
	ds_read_b128 v[198:201], v150 offset:39936
	global_load_lds_dwordx4 v[202:203], off
	v_lshl_add_u64 v[202:203], s[38:39], 0, v[130:131]
	s_mov_b32 m0, s50
	s_nop 0
	global_load_lds_dwordx4 v[202:203], off
	s_waitcnt lgkmcnt(8)
	s_barrier
	s_waitcnt lgkmcnt(0)
	s_waitcnt lgkmcnt(0)
	v_mfma_f32_16x16x32_bf16 v[124:127], v[152:155], v[168:171], v[124:127]
	v_mfma_f32_16x16x32_bf16 v[120:123], v[160:163], v[168:171], v[120:123]
	v_mfma_f32_16x16x32_bf16 v[108:111], v[152:155], v[176:179], v[108:111]
	v_mfma_f32_16x16x32_bf16 v[104:107], v[160:163], v[176:179], v[104:107]
	v_mfma_f32_16x16x32_bf16 v[92:95], v[152:155], v[186:189], v[92:95]
	v_mfma_f32_16x16x32_bf16 v[88:91], v[160:163], v[186:189], v[88:91]
	v_mfma_f32_16x16x32_bf16 v[76:79], v[152:155], v[194:197], v[76:79]
	v_mfma_f32_16x16x32_bf16 v[72:75], v[160:163], v[194:197], v[72:75]
	v_mfma_f32_16x16x32_bf16 v[124:127], v[156:159], v[172:175], v[124:127]
	v_mfma_f32_16x16x32_bf16 v[120:123], v[164:167], v[172:175], v[120:123]
	v_mfma_f32_16x16x32_bf16 v[108:111], v[156:159], v[182:185], v[108:111]
	v_mfma_f32_16x16x32_bf16 v[104:107], v[164:167], v[182:185], v[104:107]
	v_mfma_f32_16x16x32_bf16 v[92:95], v[156:159], v[190:193], v[92:95]
	v_mfma_f32_16x16x32_bf16 v[88:91], v[164:167], v[190:193], v[88:91]
	v_mfma_f32_16x16x32_bf16 v[76:79], v[156:159], v[198:201], v[76:79]
	v_mfma_f32_16x16x32_bf16 v[72:75], v[164:167], v[198:201], v[72:75]
	s_barrier
	s_add_i32 s38, 0, 0x1c000
	s_add_i32 s39, s64, s45
	v_add_u32_e32 v214, s38, v147
	v_lshl_add_u64 v[144:145], v[144:145], 0, s[12:13]
	s_mov_b32 m0, s39
	ds_read_b128 v[202:205], v214
	ds_read_b128 v[206:209], v214 offset:1024
	ds_read_b128 v[210:213], v214 offset:2048
	ds_read_b128 v[214:217], v214 offset:3072
	global_load_lds_dwordx4 v[144:145], off
	v_lshl_add_u64 v[144:145], v[218:219], 0, s[12:13]
	s_add_i32 m0, s39, 0x2000
	s_nop 0
	global_load_lds_dwordx4 v[144:145], off
	s_barrier
; #define PG8_STAGE(bufoff, gbase, voff) do { _Pragma("unroll") for (int _i = 0; _i < 2; ++_i) \
;         __builtin_amdgcn_global_load_lds((const unsigned*)((const char*)(gbase) + (voff)[_i]), (LAS unsigned*)(lds + (bufoff) + ldsw + _i * 8192), 16, 0, 0); } while (0)
; #define PG8_LDA(dst, b, h) do { _Pragma("unroll") for (int m = 0; m < 4; ++m) _Pragma("unroll") for (int k = 0; k < 2; ++k) dst[m][k] = *(const LAS bf16x8*)(lds + PG8_SA(b, h) + aoff + m * 2048 + k * 1024); } while (0)
; #define PG8_MMA(ai, bj, At, Bt) do { __builtin_amdgcn_s_setprio(1); _Pragma("unroll") for (int m = 0; m < 4; ++m) _Pragma("unroll") for (int n = 0; n < 2; ++n) _Pragma("unroll") for (int k = 0; k < 2; ++k) \
;         acc[ai][bj][m][n] = __builtin_amdgcn_mfma_f32_16x16x32_bf16(Bt[n][k], At[m][k], acc[ai][bj][m][n], 0, 0, 0); __builtin_amdgcn_s_setprio(0); } while (0)
; #define PG8_WAIT_V(n) asm volatile("s_waitcnt vmcnt(" #n ")" ::: "memory")
; #define PG8_WAIT_L(n) asm volatile("s_waitcnt lgkmcnt(" #n ")" ::: "memory")
; #define PG8_BAR __builtin_amdgcn_s_barrier()
; #define PG8_SCHED __builtin_amdgcn_sched_barrier(0)
; template <class Epi>
; DI void gemm_phase(LAS unsigned char* lds, const Gemm g, const StaticOrder& S, const Epi& E) {
;     ...
;             PG8_BAR; PG8_WAIT_L(0); PG8_MMA(0, 1, At, B1); PG8_BAR;
;             PG8_LDA(At, 1, 1); PG8_STAGE(PG8_SA(1, 0), a3, voffA);
;             PG8_BAR; PG8_WAIT_L(0); PG8_MMA(1, 0, At, B0); PG8_BAR; PG8_SCHED;
;             PG8_STAGE(PG8_SB(1, 1), b3 + hstep, voffB);
;             PG8_WAIT_V(6); PG8_BAR; PG8_MMA(1, 1, At, B1); PG8_BAR;
;         }
	s_waitcnt lgkmcnt(0)
	s_waitcnt lgkmcnt(0)
	v_mfma_f32_16x16x32_bf16 v[116:119], v[202:205], v[168:171], v[116:119]
	v_mfma_f32_16x16x32_bf16 v[112:115], v[210:213], v[168:171], v[112:115]
	v_mfma_f32_16x16x32_bf16 v[100:103], v[202:205], v[176:179], v[100:103]
	v_mfma_f32_16x16x32_bf16 v[96:99], v[210:213], v[176:179], v[96:99]
	v_mfma_f32_16x16x32_bf16 v[84:87], v[202:205], v[186:189], v[84:87]
	v_mfma_f32_16x16x32_bf16 v[80:83], v[210:213], v[186:189], v[80:83]
	v_mfma_f32_16x16x32_bf16 v[68:71], v[202:205], v[194:197], v[68:71]
	v_mfma_f32_16x16x32_bf16 v[64:67], v[210:213], v[194:197], v[64:67]
	v_mfma_f32_16x16x32_bf16 v[116:119], v[206:209], v[172:175], v[116:119]
	v_mfma_f32_16x16x32_bf16 v[112:115], v[214:217], v[172:175], v[112:115]
	v_mfma_f32_16x16x32_bf16 v[100:103], v[206:209], v[182:185], v[100:103]
	v_mfma_f32_16x16x32_bf16 v[96:99], v[214:217], v[182:185], v[96:99]
	v_mfma_f32_16x16x32_bf16 v[84:87], v[206:209], v[190:193], v[84:87]
	v_mfma_f32_16x16x32_bf16 v[80:83], v[214:217], v[190:193], v[80:83]
	v_mfma_f32_16x16x32_bf16 v[68:71], v[206:209], v[198:201], v[68:71]
	v_mfma_f32_16x16x32_bf16 v[64:67], v[214:217], v[198:201], v[64:67]
	s_mov_b32 m0, s52
	v_lshl_add_u64 v[144:145], v[220:221], 0, s[12:13]
	s_barrier
	ds_read_b128 v[168:171], v150 offset:49152
	ds_read_b128 v[172:175], v150 offset:50176
	ds_read_b128 v[176:179], v150 offset:51200
	ds_read_b128 v[182:185], v150 offset:52224
	ds_read_b128 v[186:189], v150 offset:53248
	ds_read_b128 v[190:193], v150 offset:54272
	ds_read_b128 v[194:197], v150 offset:55296
	ds_read_b128 v[198:201], v150 offset:56320
	global_load_lds_dwordx4 v[144:145], off
	v_lshl_add_u64 v[144:145], v[222:223], 0, s[12:13]
	s_mov_b32 m0, s53
	s_nop 0
	global_load_lds_dwordx4 v[144:145], off
	s_barrier
	s_waitcnt lgkmcnt(0)
	s_waitcnt lgkmcnt(0)
	v_mfma_f32_16x16x32_bf16 v[60:63], v[152:155], v[168:171], v[60:63]
	v_mfma_f32_16x16x32_bf16 v[56:59], v[160:163], v[168:171], v[56:59]
	v_mfma_f32_16x16x32_bf16 v[44:47], v[152:155], v[176:179], v[44:47]
	v_mfma_f32_16x16x32_bf16 v[40:43], v[160:163], v[176:179], v[40:43]
	v_mfma_f32_16x16x32_bf16 v[28:31], v[152:155], v[186:189], v[28:31]
	v_mfma_f32_16x16x32_bf16 v[24:27], v[160:163], v[186:189], v[24:27]
	v_mfma_f32_16x16x32_bf16 v[12:15], v[152:155], v[194:197], v[12:15]
	v_mfma_f32_16x16x32_bf16 v[8:11], v[160:163], v[194:197], v[8:11]
	v_mfma_f32_16x16x32_bf16 v[60:63], v[156:159], v[172:175], v[60:63]
	v_mfma_f32_16x16x32_bf16 v[56:59], v[164:167], v[172:175], v[56:59]
	v_mfma_f32_16x16x32_bf16 v[44:47], v[156:159], v[182:185], v[44:47]
	v_mfma_f32_16x16x32_bf16 v[40:43], v[164:167], v[182:185], v[40:43]
	v_mfma_f32_16x16x32_bf16 v[28:31], v[156:159], v[190:193], v[28:31]
	v_mfma_f32_16x16x32_bf16 v[24:27], v[164:167], v[190:193], v[24:27]
	v_mfma_f32_16x16x32_bf16 v[12:15], v[156:159], v[198:201], v[12:15]
	v_mfma_f32_16x16x32_bf16 v[8:11], v[164:167], v[198:201], v[8:11]
	s_barrier
	s_add_u32 s36, s36, 0x40080
	s_addc_u32 s37, s37, 0
	s_add_i32 s38, s38, s45
	v_lshl_add_u64 v[144:145], s[36:37], 0, v[132:133]
	s_mov_b32 m0, s38
	s_nop 0
	global_load_lds_dwordx4 v[144:145], off
	v_lshl_add_u64 v[144:145], s[36:37], 0, v[128:129]
	s_add_i32 m0, s38, 0x2000
	s_nop 0
	global_load_lds_dwordx4 v[144:145], off
	s_waitcnt vmcnt(6)
	s_barrier
	v_mfma_f32_16x16x32_bf16 v[52:55], v[202:205], v[168:171], v[52:55]
	v_mfma_f32_16x16x32_bf16 v[48:51], v[210:213], v[168:171], v[48:51]
	v_mfma_f32_16x16x32_bf16 v[36:39], v[202:205], v[176:179], v[36:39]
	v_mfma_f32_16x16x32_bf16 v[32:35], v[210:213], v[176:179], v[32:35]
	v_mfma_f32_16x16x32_bf16 v[20:23], v[202:205], v[186:189], v[20:23]
	v_mfma_f32_16x16x32_bf16 v[16:19], v[210:213], v[186:189], v[16:19]
	v_mfma_f32_16x16x32_bf16 v[4:7], v[202:205], v[194:197], v[4:7]
	v_mfma_f32_16x16x32_bf16 v[0:3], v[210:213], v[194:197], v[0:3]
	v_mfma_f32_16x16x32_bf16 v[52:55], v[206:209], v[172:175], v[52:55]
	v_mfma_f32_16x16x32_bf16 v[48:51], v[214:217], v[172:175], v[48:51]
	v_mfma_f32_16x16x32_bf16 v[36:39], v[206:209], v[182:185], v[36:39]
	v_mfma_f32_16x16x32_bf16 v[32:35], v[214:217], v[182:185], v[32:35]
	v_mfma_f32_16x16x32_bf16 v[20:23], v[206:209], v[190:193], v[20:23]
	v_mfma_f32_16x16x32_bf16 v[16:19], v[214:217], v[190:193], v[16:19]
	v_mfma_f32_16x16x32_bf16 v[4:7], v[206:209], v[198:201], v[4:7]
	v_mfma_f32_16x16x32_bf16 v[0:3], v[214:217], v[198:201], v[0:3]
	s_add_i32 s63, s63, 2
	s_add_u32 s24, s24, 0x100
	s_addc_u32 s25, s25, 0
	s_add_u32 s61, s61, 0x100
	s_addc_u32 s62, s62, 0
	s_cmp_gt_u32 s63, 13
	s_barrier

; #define PG8_STAGE(bufoff, gbase, voff) do { _Pragma("unroll") for (int _i = 0; _i < 2; ++_i) \
;         __builtin_amdgcn_global_load_lds((const unsigned*)((const char*)(gbase) + (voff)[_i]), (LAS unsigned*)(lds + (bufoff) + ldsw + _i * 8192), 16, 0, 0); } while (0)
; #define PG8_LDA(dst, b, h) do { _Pragma("unroll") for (int m = 0; m < 4; ++m) _Pragma("unroll") for (int k = 0; k < 2; ++k) dst[m][k] = *(const LAS bf16x8*)(lds + PG8_SA(b, h) + aoff + m * 2048 + k * 1024); } while (0)
; #define PG8_LDB(dst, b, h) do { _Pragma("unroll") for (int n = 0; n < 2; ++n) _Pragma("unroll") for (int k = 0; k < 2; ++k) dst[n][k] = *(const LAS bf16x8*)(lds + PG8_SB(b, h) + boff + n * 2048 + k * 1024); } while (0)
; #define PG8_MMA(ai, bj, At, Bt) do { __builtin_amdgcn_s_setprio(1); _Pragma("unroll") for (int m = 0; m < 4; ++m) _Pragma("unroll") for (int n = 0; n < 2; ++n) _Pragma("unroll") for (int k = 0; k < 2; ++k) \
;         acc[ai][bj][m][n] = __builtin_amdgcn_mfma_f32_16x16x32_bf16(Bt[n][k], At[m][k], acc[ai][bj][m][n], 0, 0, 0); __builtin_amdgcn_s_setprio(0); } while (0)
; #define PG8_WAIT_L(n) asm volatile("s_waitcnt lgkmcnt(" #n ")" ::: "memory")
; #define PG8_BAR __builtin_amdgcn_s_barrier()
; #define PG8_SCHED __builtin_amdgcn_sched_barrier(0)
; template <class Epi>
; DI void gemm_phase(LAS unsigned char* lds, const Gemm g, const StaticOrder& S, const Epi& E) {
;     ...
;         for (int t = 0; t < nt; t += 2) {
;             const bool last = (t == nt - 2);
;             const char* a1 = cA + (size_t)(t + 1) * kstep;
;             const char* a2 = last ? nA : cA + (size_t)(t + 2) * kstep; const char* b2 = last ? nB : cB + (size_t)(t + 2) * kstep;
;             const char* a3 = a2 + kstep; const char* b3 = b2 + kstep;
;             PG8_LDB(B0, 0, 0); PG8_SCHED; PG8_LDA(At, 0, 0); PG8_STAGE(PG8_SA(1, 1), a1 + hstep, voffA);
;             PG8_WAIT_L(8); PG8_BAR; PG8_WAIT_L(0); PG8_MMA(0, 0, At, B0); PG8_BAR; PG8_SCHED;
;             PG8_LDB(B1, 0, 1); PG8_STAGE(PG8_SB(0, 0), b2, voffB);
;             PG8_BAR; PG8_WAIT_L(0); PG8_MMA(0, 1, At, B1); PG8_BAR;
;             PG8_LDA(At, 0, 1); PG8_STAGE(PG8_SA(0, 0), a2, voffA);
;             PG8_BAR; PG8_WAIT_L(0); PG8_MMA(1, 0, At, B0); PG8_BAR; PG8_SCHED;
.LBB0_927:
	s_add_u32 s36, s36, 0xb0080
	s_addc_u32 s37, s37, 0
	s_add_u32 s71, s38, 0x100
	s_addc_u32 s72, s39, 0
	s_mov_b32 s73, -2
	ds_read_b128 v[128:131], v173
	ds_read_b128 v[132:135], v173 offset:1024
	ds_read_b128 v[136:139], v173 offset:2048
	ds_read_b128 v[140:143], v173 offset:3072
	s_add_u32 s38, s36, 0xfff50080
	s_addc_u32 s39, s37, -1
	s_cmp_eq_u32 s73, 40
	s_cselect_b32 s41, s7, s39
	s_cselect_b32 s40, s6, s38
	s_cselect_b32 s39, s9, s72
	s_cselect_b32 s38, s8, s71
	v_lshl_add_u64 v[168:169], s[36:37], 0, v[156:157]
	s_add_i32 m0, s49, 0xc000
	ds_read_b128 v[144:147], v174
	ds_read_b128 v[164:167], v174 offset:1024
	ds_read_b128 v[176:179], v174 offset:2048
	ds_read_b128 v[182:185], v174 offset:3072
	ds_read_b128 v[186:189], v174 offset:4096
	ds_read_b128 v[190:193], v174 offset:5120
	ds_read_b128 v[194:197], v174 offset:6144
	ds_read_b128 v[198:201], v174 offset:7168
	global_load_lds_dwordx4 v[168:169], off
	v_lshl_add_u64 v[168:169], s[36:37], 0, v[158:159]
	s_add_i32 m0, s49, 0xe000
	s_nop 0
	global_load_lds_dwordx4 v[168:169], off
	s_waitcnt lgkmcnt(8)
	s_barrier
	s_waitcnt lgkmcnt(0)
	s_waitcnt lgkmcnt(0)
	v_mfma_f32_16x16x32_bf16 v[124:127], v[128:131], v[144:147], 0
	v_mfma_f32_16x16x32_bf16 v[120:123], v[136:139], v[144:147], 0
	v_mfma_f32_16x16x32_bf16 v[116:119], v[128:131], v[176:179], 0
	v_mfma_f32_16x16x32_bf16 v[108:111], v[136:139], v[176:179], 0
	v_mfma_f32_16x16x32_bf16 v[92:95], v[128:131], v[186:189], 0
	v_mfma_f32_16x16x32_bf16 v[88:91], v[136:139], v[186:189], 0
	v_mfma_f32_16x16x32_bf16 v[76:79], v[128:131], v[194:197], 0
	v_mfma_f32_16x16x32_bf16 v[72:75], v[136:139], v[194:197], 0
	v_mfma_f32_16x16x32_bf16 v[124:127], v[132:135], v[164:167], v[124:127]
	v_mfma_f32_16x16x32_bf16 v[120:123], v[140:143], v[164:167], v[120:123]
	v_mfma_f32_16x16x32_bf16 v[116:119], v[132:135], v[182:185], v[116:119]
	v_mfma_f32_16x16x32_bf16 v[108:111], v[140:143], v[182:185], v[108:111]
	v_mfma_f32_16x16x32_bf16 v[92:95], v[132:135], v[190:193], v[92:95]
	v_mfma_f32_16x16x32_bf16 v[88:91], v[140:143], v[190:193], v[88:91]
	v_mfma_f32_16x16x32_bf16 v[76:79], v[132:135], v[198:201], v[76:79]
	v_mfma_f32_16x16x32_bf16 v[72:75], v[140:143], v[198:201], v[72:75]
	s_barrier
	s_add_i32 s74, s59, s48
	v_lshl_add_u64 v[168:169], s[38:39], 0, v[150:151]
	s_mov_b32 m0, s74
	ds_read_b128 v[202:205], v175
	ds_read_b128 v[206:209], v175 offset:1024
	ds_read_b128 v[210:213], v175 offset:2048
	ds_read_b128 v[214:217], v175 offset:3072
	global_load_lds_dwordx4 v[168:169], off
	v_lshl_add_u64 v[218:219], s[38:39], 0, v[154:155]
	s_add_i32 m0, s74, 0x2000
	s_nop 0
	global_load_lds_dwordx4 v[218:219], off
	s_barrier
	s_waitcnt lgkmcnt(0)
	s_waitcnt lgkmcnt(0)
	v_mfma_f32_16x16x32_bf16 v[112:115], v[202:205], v[144:147], 0
	v_mfma_f32_16x16x32_bf16 v[104:107], v[210:213], v[144:147], 0
	v_mfma_f32_16x16x32_bf16 v[100:103], v[202:205], v[176:179], 0
	v_mfma_f32_16x16x32_bf16 v[96:99], v[210:213], v[176:179], 0
	v_mfma_f32_16x16x32_bf16 v[84:87], v[202:205], v[186:189], 0
	v_mfma_f32_16x16x32_bf16 v[80:83], v[210:213], v[186:189], 0
	v_mfma_f32_16x16x32_bf16 v[68:71], v[202:205], v[194:197], 0
	v_mfma_f32_16x16x32_bf16 v[64:67], v[210:213], v[194:197], 0
	v_mfma_f32_16x16x32_bf16 v[112:115], v[206:209], v[164:167], v[112:115]
	v_mfma_f32_16x16x32_bf16 v[104:107], v[214:217], v[164:167], v[104:107]
	v_mfma_f32_16x16x32_bf16 v[100:103], v[206:209], v[182:185], v[100:103]
	v_mfma_f32_16x16x32_bf16 v[96:99], v[214:217], v[182:185], v[96:99]
	v_mfma_f32_16x16x32_bf16 v[84:87], v[206:209], v[190:193], v[84:87]
	v_mfma_f32_16x16x32_bf16 v[80:83], v[214:217], v[190:193], v[80:83]
	v_mfma_f32_16x16x32_bf16 v[68:71], v[206:209], v[198:201], v[68:71]
	v_mfma_f32_16x16x32_bf16 v[64:67], v[214:217], v[198:201], v[64:67]
	s_mov_b32 m0, s49
	v_lshl_add_u64 v[220:221], s[40:41], 0, v[148:149]
	s_barrier
	ds_read_b128 v[144:147], v174 offset:16384
	ds_read_b128 v[164:167], v174 offset:17408
	ds_read_b128 v[176:179], v174 offset:18432
	ds_read_b128 v[182:185], v174 offset:19456
	ds_read_b128 v[186:189], v174 offset:20480
	ds_read_b128 v[190:193], v174 offset:21504
	ds_read_b128 v[194:197], v174 offset:22528
	ds_read_b128 v[198:201], v174 offset:23552
	global_load_lds_dwordx4 v[220:221], off
	v_lshl_add_u64 v[222:223], s[40:41], 0, v[152:153]
	s_mov_b32 m0, s50
	s_nop 0
	global_load_lds_dwordx4 v[222:223], off
	s_barrier
	s_waitcnt lgkmcnt(0)
	s_waitcnt lgkmcnt(0)
	v_mfma_f32_16x16x32_bf16 v[60:63], v[128:131], v[144:147], 0
	v_mfma_f32_16x16x32_bf16 v[56:59], v[136:139], v[144:147], 0
	v_mfma_f32_16x16x32_bf16 v[44:47], v[128:131], v[176:179], 0
	v_mfma_f32_16x16x32_bf16 v[40:43], v[136:139], v[176:179], 0
	v_mfma_f32_16x16x32_bf16 v[36:39], v[128:131], v[186:189], 0
	v_mfma_f32_16x16x32_bf16 v[32:35], v[136:139], v[186:189], 0
	v_mfma_f32_16x16x32_bf16 v[20:23], v[128:131], v[194:197], 0
	v_mfma_f32_16x16x32_bf16 v[16:19], v[136:139], v[194:197], 0
	v_mfma_f32_16x16x32_bf16 v[60:63], v[132:135], v[164:167], v[60:63]
	v_mfma_f32_16x16x32_bf16 v[56:59], v[140:143], v[164:167], v[56:59]
	v_mfma_f32_16x16x32_bf16 v[44:47], v[132:135], v[182:185], v[44:47]
	v_mfma_f32_16x16x32_bf16 v[40:43], v[140:143], v[182:185], v[40:43]
	v_mfma_f32_16x16x32_bf16 v[36:39], v[132:135], v[190:193], v[36:39]
	v_mfma_f32_16x16x32_bf16 v[32:35], v[140:143], v[190:193], v[32:35]
	v_mfma_f32_16x16x32_bf16 v[20:23], v[132:135], v[198:201], v[20:23]
	v_mfma_f32_16x16x32_bf16 v[16:19], v[140:143], v[198:201], v[16:19]
	s_barrier
; #define PG8_STAGE(bufoff, gbase, voff) do { _Pragma("unroll") for (int _i = 0; _i < 2; ++_i) \
;         __builtin_amdgcn_global_load_lds((const unsigned*)((const char*)(gbase) + (voff)[_i]), (LAS unsigned*)(lds + (bufoff) + ldsw + _i * 8192), 16, 0, 0); } while (0)
; #define PG8_LDA(dst, b, h) do { _Pragma("unroll") for (int m = 0; m < 4; ++m) _Pragma("unroll") for (int k = 0; k < 2; ++k) dst[m][k] = *(const LAS bf16x8*)(lds + PG8_SA(b, h) + aoff + m * 2048 + k * 1024); } while (0)
; #define PG8_LDB(dst, b, h) do { _Pragma("unroll") for (int n = 0; n < 2; ++n) _Pragma("unroll") for (int k = 0; k < 2; ++k) dst[n][k] = *(const LAS bf16x8*)(lds + PG8_SB(b, h) + boff + n * 2048 + k * 1024); } while (0)
; #define PG8_MMA(ai, bj, At, Bt) do { __builtin_amdgcn_s_setprio(1); _Pragma("unroll") for (int m = 0; m < 4; ++m) _Pragma("unroll") for (int n = 0; n < 2; ++n) _Pragma("unroll") for (int k = 0; k < 2; ++k) \
;         acc[ai][bj][m][n] = __builtin_amdgcn_mfma_f32_16x16x32_bf16(Bt[n][k], At[m][k], acc[ai][bj][m][n], 0, 0, 0); __builtin_amdgcn_s_setprio(0); } while (0)
; #define PG8_WAIT_V(n) asm volatile("s_waitcnt vmcnt(" #n ")" ::: "memory")
; #define PG8_WAIT_L(n) asm volatile("s_waitcnt lgkmcnt(" #n ")" ::: "memory")
; #define PG8_BAR __builtin_amdgcn_s_barrier()
; #define PG8_SCHED __builtin_amdgcn_sched_barrier(0)
; template <class Epi>
; DI void gemm_phase(LAS unsigned char* lds, const Gemm g, const StaticOrder& S, const Epi& E) {
;     ...
;             PG8_STAGE(PG8_SB(0, 1), b2 + hstep, voffB);
;             PG8_WAIT_V(6); PG8_BAR; PG8_MMA(1, 1, At, B1); PG8_BAR;
;             PG8_LDB(B0, 1, 0); PG8_SCHED; PG8_LDA(At, 1, 0); PG8_STAGE(PG8_SA(0, 1), a2 + hstep, voffA);
;             PG8_WAIT_L(8); PG8_BAR; PG8_WAIT_L(0); PG8_MMA(0, 0, At, B0); PG8_BAR; PG8_SCHED;
;             PG8_LDB(B1, 1, 1); PG8_STAGE(PG8_SB(1, 0), b3, voffB);
	s_add_u32 s74, s38, 0xb0000
	s_addc_u32 s75, s39, 0
	s_add_i32 s76, s60, s48
	v_lshl_add_u64 v[128:129], s[74:75], 0, v[150:151]
	s_mov_b32 m0, s76
	s_nop 0
	global_load_lds_dwordx4 v[128:129], off
	v_lshl_add_u64 v[128:129], s[74:75], 0, v[154:155]
	s_add_i32 m0, s76, 0x2000
	s_nop 0
	global_load_lds_dwordx4 v[128:129], off
	s_waitcnt vmcnt(6)
	s_barrier
	v_mfma_f32_16x16x32_bf16 v[52:55], v[202:205], v[144:147], 0
	v_mfma_f32_16x16x32_bf16 v[48:51], v[210:213], v[144:147], 0
	v_mfma_f32_16x16x32_bf16 v[28:31], v[202:205], v[176:179], 0
	v_mfma_f32_16x16x32_bf16 v[24:27], v[210:213], v[176:179], 0
	v_mfma_f32_16x16x32_bf16 v[12:15], v[202:205], v[186:189], 0
	v_mfma_f32_16x16x32_bf16 v[8:11], v[210:213], v[186:189], 0
	v_mfma_f32_16x16x32_bf16 v[4:7], v[202:205], v[194:197], 0
	v_mfma_f32_16x16x32_bf16 v[0:3], v[210:213], v[194:197], 0
	v_mfma_f32_16x16x32_bf16 v[52:55], v[206:209], v[164:167], v[52:55]
	v_mfma_f32_16x16x32_bf16 v[48:51], v[214:217], v[164:167], v[48:51]
	v_mfma_f32_16x16x32_bf16 v[28:31], v[206:209], v[182:185], v[28:31]
	v_mfma_f32_16x16x32_bf16 v[24:27], v[214:217], v[182:185], v[24:27]
	v_mfma_f32_16x16x32_bf16 v[12:15], v[206:209], v[190:193], v[12:15]
	v_mfma_f32_16x16x32_bf16 v[8:11], v[214:217], v[190:193], v[8:11]
	v_mfma_f32_16x16x32_bf16 v[4:7], v[206:209], v[198:201], v[4:7]
	v_mfma_f32_16x16x32_bf16 v[0:3], v[214:217], v[198:201], v[0:3]
	s_add_i32 s74, 0, 0x18000
	v_add_u32_e32 v140, s74, v171
	s_barrier
	ds_read_b128 v[128:131], v140
	ds_read_b128 v[132:135], v140 offset:1024
	ds_read_b128 v[136:139], v140 offset:2048
	ds_read_b128 v[140:143], v140 offset:3072
	s_add_u32 s40, s40, 0xb0000
	s_addc_u32 s41, s41, 0
	s_mov_b32 m0, s51
	v_lshl_add_u64 v[202:203], s[40:41], 0, v[148:149]
	ds_read_b128 v[144:147], v174 offset:32768
	ds_read_b128 v[164:167], v174 offset:33792
	ds_read_b128 v[176:179], v174 offset:34816
	ds_read_b128 v[182:185], v174 offset:35840
	ds_read_b128 v[186:189], v174 offset:36864
	ds_read_b128 v[190:193], v174 offset:37888
	ds_read_b128 v[194:197], v174 offset:38912
	ds_read_b128 v[198:201], v174 offset:39936
	global_load_lds_dwordx4 v[202:203], off
	v_lshl_add_u64 v[202:203], s[40:41], 0, v[152:153]
	s_mov_b32 m0, s52
	s_nop 0
	global_load_lds_dwordx4 v[202:203], off
	s_waitcnt lgkmcnt(8)
	s_barrier
	s_waitcnt lgkmcnt(0)
	s_waitcnt lgkmcnt(0)
	v_mfma_f32_16x16x32_bf16 v[124:127], v[128:131], v[144:147], v[124:127]
	v_mfma_f32_16x16x32_bf16 v[120:123], v[136:139], v[144:147], v[120:123]
	v_mfma_f32_16x16x32_bf16 v[116:119], v[128:131], v[176:179], v[116:119]
	v_mfma_f32_16x16x32_bf16 v[108:111], v[136:139], v[176:179], v[108:111]
	v_mfma_f32_16x16x32_bf16 v[92:95], v[128:131], v[186:189], v[92:95]
	v_mfma_f32_16x16x32_bf16 v[88:91], v[136:139], v[186:189], v[88:91]
	v_mfma_f32_16x16x32_bf16 v[76:79], v[128:131], v[194:197], v[76:79]
	v_mfma_f32_16x16x32_bf16 v[72:75], v[136:139], v[194:197], v[72:75]
	v_mfma_f32_16x16x32_bf16 v[124:127], v[132:135], v[164:167], v[124:127]
	v_mfma_f32_16x16x32_bf16 v[120:123], v[140:143], v[164:167], v[120:123]
	v_mfma_f32_16x16x32_bf16 v[116:119], v[132:135], v[182:185], v[116:119]
	v_mfma_f32_16x16x32_bf16 v[108:111], v[140:143], v[182:185], v[108:111]
	v_mfma_f32_16x16x32_bf16 v[92:95], v[132:135], v[190:193], v[92:95]
	v_mfma_f32_16x16x32_bf16 v[88:91], v[140:143], v[190:193], v[88:91]
	v_mfma_f32_16x16x32_bf16 v[76:79], v[132:135], v[198:201], v[76:79]
	v_mfma_f32_16x16x32_bf16 v[72:75], v[140:143], v[198:201], v[72:75]
	s_barrier
	s_add_i32 s40, 0, 0x1c000
	s_add_i32 s41, s74, s48
	v_add_u32_e32 v214, s40, v171
	v_lshl_add_u64 v[168:169], v[168:169], 0, s[16:17]
	s_mov_b32 m0, s41
	ds_read_b128 v[202:205], v214
	ds_read_b128 v[206:209], v214 offset:1024
	ds_read_b128 v[210:213], v214 offset:2048
	ds_read_b128 v[214:217], v214 offset:3072
	global_load_lds_dwordx4 v[168:169], off
	v_lshl_add_u64 v[168:169], v[218:219], 0, s[16:17]
	s_add_i32 m0, s41, 0x2000
	s_nop 0
	global_load_lds_dwordx4 v[168:169], off
	s_barrier
; #define PG8_STAGE(bufoff, gbase, voff) do { _Pragma("unroll") for (int _i = 0; _i < 2; ++_i) \
;         __builtin_amdgcn_global_load_lds((const unsigned*)((const char*)(gbase) + (voff)[_i]), (LAS unsigned*)(lds + (bufoff) + ldsw + _i * 8192), 16, 0, 0); } while (0)
; #define PG8_LDA(dst, b, h) do { _Pragma("unroll") for (int m = 0; m < 4; ++m) _Pragma("unroll") for (int k = 0; k < 2; ++k) dst[m][k] = *(const LAS bf16x8*)(lds + PG8_SA(b, h) + aoff + m * 2048 + k * 1024); } while (0)
; #define PG8_MMA(ai, bj, At, Bt) do { __builtin_amdgcn_s_setprio(1); _Pragma("unroll") for (int m = 0; m < 4; ++m) _Pragma("unroll") for (int n = 0; n < 2; ++n) _Pragma("unroll") for (int k = 0; k < 2; ++k) \
;         acc[ai][bj][m][n] = __builtin_amdgcn_mfma_f32_16x16x32_bf16(Bt[n][k], At[m][k], acc[ai][bj][m][n], 0, 0, 0); __builtin_amdgcn_s_setprio(0); } while (0)
; #define PG8_WAIT_V(n) asm volatile("s_waitcnt vmcnt(" #n ")" ::: "memory")
; #define PG8_WAIT_L(n) asm volatile("s_waitcnt lgkmcnt(" #n ")" ::: "memory")
; #define PG8_BAR __builtin_amdgcn_s_barrier()
; #define PG8_SCHED __builtin_amdgcn_sched_barrier(0)
; template <class Epi>
; DI void gemm_phase(LAS unsigned char* lds, const Gemm g, const StaticOrder& S, const Epi& E) {
;     ...
;             PG8_BAR; PG8_WAIT_L(0); PG8_MMA(0, 1, At, B1); PG8_BAR;
;             PG8_LDA(At, 1, 1); PG8_STAGE(PG8_SA(1, 0), a3, voffA);
;             PG8_BAR; PG8_WAIT_L(0); PG8_MMA(1, 0, At, B0); PG8_BAR; PG8_SCHED;
;             PG8_STAGE(PG8_SB(1, 1), b3 + hstep, voffB);
;             PG8_WAIT_V(6); PG8_BAR; PG8_MMA(1, 1, At, B1); PG8_BAR;
;         }
	s_waitcnt lgkmcnt(0)
	s_waitcnt lgkmcnt(0)
	v_mfma_f32_16x16x32_bf16 v[112:115], v[202:205], v[144:147], v[112:115]
	v_mfma_f32_16x16x32_bf16 v[104:107], v[210:213], v[144:147], v[104:107]
	v_mfma_f32_16x16x32_bf16 v[100:103], v[202:205], v[176:179], v[100:103]
	v_mfma_f32_16x16x32_bf16 v[96:99], v[210:213], v[176:179], v[96:99]
	v_mfma_f32_16x16x32_bf16 v[84:87], v[202:205], v[186:189], v[84:87]
	v_mfma_f32_16x16x32_bf16 v[80:83], v[210:213], v[186:189], v[80:83]
	v_mfma_f32_16x16x32_bf16 v[68:71], v[202:205], v[194:197], v[68:71]
	v_mfma_f32_16x16x32_bf16 v[64:67], v[210:213], v[194:197], v[64:67]
	v_mfma_f32_16x16x32_bf16 v[112:115], v[206:209], v[164:167], v[112:115]
	v_mfma_f32_16x16x32_bf16 v[104:107], v[214:217], v[164:167], v[104:107]
	v_mfma_f32_16x16x32_bf16 v[100:103], v[206:209], v[182:185], v[100:103]
	v_mfma_f32_16x16x32_bf16 v[96:99], v[214:217], v[182:185], v[96:99]
	v_mfma_f32_16x16x32_bf16 v[84:87], v[206:209], v[190:193], v[84:87]
	v_mfma_f32_16x16x32_bf16 v[80:83], v[214:217], v[190:193], v[80:83]
	v_mfma_f32_16x16x32_bf16 v[68:71], v[206:209], v[198:201], v[68:71]
	v_mfma_f32_16x16x32_bf16 v[64:67], v[214:217], v[198:201], v[64:67]
	s_mov_b32 m0, s56
	v_lshl_add_u64 v[168:169], v[220:221], 0, s[16:17]
	s_barrier
	ds_read_b128 v[144:147], v174 offset:49152
	ds_read_b128 v[164:167], v174 offset:50176
	ds_read_b128 v[176:179], v174 offset:51200
	ds_read_b128 v[182:185], v174 offset:52224
	ds_read_b128 v[186:189], v174 offset:53248
	ds_read_b128 v[190:193], v174 offset:54272
	ds_read_b128 v[194:197], v174 offset:55296
	ds_read_b128 v[198:201], v174 offset:56320
	global_load_lds_dwordx4 v[168:169], off
	v_lshl_add_u64 v[168:169], v[222:223], 0, s[16:17]
	s_mov_b32 m0, s57
	s_nop 0
	global_load_lds_dwordx4 v[168:169], off
	s_barrier
	s_waitcnt lgkmcnt(0)
	s_waitcnt lgkmcnt(0)
	v_mfma_f32_16x16x32_bf16 v[60:63], v[128:131], v[144:147], v[60:63]
	v_mfma_f32_16x16x32_bf16 v[56:59], v[136:139], v[144:147], v[56:59]
	v_mfma_f32_16x16x32_bf16 v[44:47], v[128:131], v[176:179], v[44:47]
	v_mfma_f32_16x16x32_bf16 v[40:43], v[136:139], v[176:179], v[40:43]
	v_mfma_f32_16x16x32_bf16 v[36:39], v[128:131], v[186:189], v[36:39]
	v_mfma_f32_16x16x32_bf16 v[32:35], v[136:139], v[186:189], v[32:35]
	v_mfma_f32_16x16x32_bf16 v[20:23], v[128:131], v[194:197], v[20:23]
	v_mfma_f32_16x16x32_bf16 v[16:19], v[136:139], v[194:197], v[16:19]
	v_mfma_f32_16x16x32_bf16 v[60:63], v[132:135], v[164:167], v[60:63]
	v_mfma_f32_16x16x32_bf16 v[56:59], v[140:143], v[164:167], v[56:59]
	v_mfma_f32_16x16x32_bf16 v[44:47], v[132:135], v[182:185], v[44:47]
	v_mfma_f32_16x16x32_bf16 v[40:43], v[140:143], v[182:185], v[40:43]
	v_mfma_f32_16x16x32_bf16 v[36:39], v[132:135], v[190:193], v[36:39]
	v_mfma_f32_16x16x32_bf16 v[32:35], v[140:143], v[190:193], v[32:35]
	v_mfma_f32_16x16x32_bf16 v[20:23], v[132:135], v[198:201], v[20:23]
	v_mfma_f32_16x16x32_bf16 v[16:19], v[140:143], v[198:201], v[16:19]
	s_barrier
	s_add_u32 s38, s38, 0xb0080
	s_addc_u32 s39, s39, 0
	s_add_i32 s40, s40, s48
	v_lshl_add_u64 v[128:129], s[38:39], 0, v[150:151]
	s_mov_b32 m0, s40
	s_nop 0
	global_load_lds_dwordx4 v[128:129], off
	v_lshl_add_u64 v[128:129], s[38:39], 0, v[154:155]
	s_add_i32 m0, s40, 0x2000
	s_nop 0
	global_load_lds_dwordx4 v[128:129], off
	s_waitcnt vmcnt(6)
	s_barrier
	v_mfma_f32_16x16x32_bf16 v[52:55], v[202:205], v[144:147], v[52:55]
	v_mfma_f32_16x16x32_bf16 v[48:51], v[210:213], v[144:147], v[48:51]
	v_mfma_f32_16x16x32_bf16 v[28:31], v[202:205], v[176:179], v[28:31]
	v_mfma_f32_16x16x32_bf16 v[24:27], v[210:213], v[176:179], v[24:27]
	v_mfma_f32_16x16x32_bf16 v[12:15], v[202:205], v[186:189], v[12:15]
	v_mfma_f32_16x16x32_bf16 v[8:11], v[210:213], v[186:189], v[8:11]
	v_mfma_f32_16x16x32_bf16 v[4:7], v[202:205], v[194:197], v[4:7]
	v_mfma_f32_16x16x32_bf16 v[0:3], v[210:213], v[194:197], v[0:3]
	v_mfma_f32_16x16x32_bf16 v[52:55], v[206:209], v[164:167], v[52:55]
	v_mfma_f32_16x16x32_bf16 v[48:51], v[214:217], v[164:167], v[48:51]
	v_mfma_f32_16x16x32_bf16 v[28:31], v[206:209], v[182:185], v[28:31]
	v_mfma_f32_16x16x32_bf16 v[24:27], v[214:217], v[182:185], v[24:27]
	v_mfma_f32_16x16x32_bf16 v[12:15], v[206:209], v[190:193], v[12:15]
	v_mfma_f32_16x16x32_bf16 v[8:11], v[214:217], v[190:193], v[8:11]
	v_mfma_f32_16x16x32_bf16 v[4:7], v[206:209], v[198:201], v[4:7]
	v_mfma_f32_16x16x32_bf16 v[0:3], v[214:217], v[198:201], v[0:3]
	s_add_i32 s73, s73, 2
	s_add_u32 s36, s36, 0x100
	s_addc_u32 s37, s37, 0
	s_add_u32 s71, s71, 0x100
	s_addc_u32 s72, s72, 0
	s_cmp_gt_u32 s73, 41
	s_barrier
